# FFN-down GEMM second round as 256 half tiles (128x256) on all workgroups instead of 128 full tiles on half of them
# speedup vs baseline: 1.0118x; 1.0118x over previous
_Z14fwd_megakernel6Params:
	v_and_b32_e32 v163, 0x3ff, v0
	v_writelane_b32 v254, s2, 0
	s_add_u32 s2, s0, 0x120
	s_addc_u32 s3, s1, 0
	v_writelane_b32 v254, s2, 1
	v_and_b32_e32 v0, 0x3fffffff, v0
	v_mbcnt_lo_u32_b32 v203, -1, 0
	v_writelane_b32 v254, s3, 2
	v_writelane_b32 v254, s0, 3
	v_mbcnt_hi_u32_b32 v204, -1, v203
	v_and_b32_e32 v205, 64, v204
	v_writelane_b32 v254, s1, 4
	s_load_dword s0, s[0:1], 0x120
	s_mov_b32 s1, 0
	s_movk_i32 s33, 0x6000
	v_mov_b32_e32 v1, 0
	v_mov_b32_e32 v162, 0x358637bd
	s_waitcnt lgkmcnt(0)
	v_writelane_b32 v254, s0, 5
	s_cmp_eq_u32 s0, 0x100
	s_cselect_b32 s2, 1, 0
	v_writelane_b32 v255, s2, 41
	s_add_i32 s0, 0, 0x23fc0
	v_writelane_b32 v254, s0, 6
	s_add_i32 s0, 0, 0x19800
	v_writelane_b32 v254, s0, 7
	s_add_i32 s0, 0, 0x22400
	v_writelane_b32 v254, s0, 8
	s_add_i32 s0, 0, 0x22200
	v_writelane_b32 v254, s0, 9
	s_add_i32 s0, 0, 0x22000
	v_writelane_b32 v254, s0, 10
	s_add_i32 s0, 0, 0x11000
	v_writelane_b32 v254, s0, 11
	s_add_i32 s0, 0, 0x8800
	v_writelane_b32 v254, s0, 12
	s_add_i32 s0, 0, 0x225fc
	v_writelane_b32 v254, s0, 13
	s_add_i32 s0, 0, 0x221fc
	v_writelane_b32 v254, s0, 14
	s_add_i32 s0, 0, 0x23fe0
	v_writelane_b32 v254, s0, 15
	s_add_i32 s0, 0, 0x23fe4
	v_writelane_b32 v254, s0, 16
	s_mov_b32 s0, 0
	v_writelane_b32 v254, s0, 17
	v_writelane_b32 v254, s0, 18
	v_writelane_b32 v254, s0, 19
	s_mov_b32 s94, 0x30000
	v_mov_b32_e32 v171, 1
	v_writelane_b32 v254, s1, 20
	v_cmp_eq_u32_e64 s[0:1], 0, v0
	v_mov_b32_e32 v202, 0x2000
	v_add_u32_e32 v206, 64, v205
	v_writelane_b32 v254, s0, 21
	v_xor_b32_e32 v207, 32, v204
	v_xor_b32_e32 v208, 16, v204
	v_writelane_b32 v254, s1, 22
	s_mov_b64 s[0:1], 0
	v_writelane_b32 v254, s0, 23
	v_xor_b32_e32 v209, 8, v204
	v_xor_b32_e32 v220, 4, v204
	v_xor_b32_e32 v217, 2, v204
	v_xor_b32_e32 v212, 1, v204
	v_mov_b32_e32 v213, 0x7ff
	v_mov_b32_e32 v214, 0xff
	v_mov_b32_e32 v215, 0xffffff03
	v_mov_b64_e32 v[164:165], 0x17f
	v_mov_b64_e32 v[166:167], 0x180
	v_mov_b32_e32 v168, 0xff800000
	v_mov_b32_e32 v216, 0x800
	v_mov_b32_e32 v170, 0x3ecc95a3
	v_mov_b32_e32 v218, 0x7f800000
	v_mov_b32_e32 v219, 0x7fc00000
	v_mov_b32_e32 v221, 0x100
	v_mov_b32_e32 v222, 0x3f549a78
	v_mov_b32_e32 v223, 0x3fd49a78
	v_mov_b32_e32 v224, 0x42800000
	v_not_b32_e32 v225, 63
	v_not_b32_e32 v226, 31
	v_mov_b32_e32 v227, 0x6000
	v_mov_b32_e32 v228, 0x5000
	s_mov_b32 s95, 0x48000
	v_writelane_b32 v254, s1, 24
	s_mov_b64 s[92:93], 0x80
	s_branch .LBB0_3

.LBB0_657:
	s_or_b64 exec, exec, s[90:91]
	s_andn2_b64 vcc, exec, s[96:97]
	s_waitcnt lgkmcnt(0)
	s_barrier
	s_cbranch_vccnz .LBB0_663
	global_load_dwordx4 v[2:5], v[112:113], off offset:1024
	global_load_dwordx4 v[6:9], v[114:115], off offset:1024
	global_load_dwordx4 v[10:13], v[116:117], off offset:1024
	global_load_dwordx4 v[14:17], v[118:119], off offset:1024
	s_and_saveexec_b64 s[90:91], s[8:9]
	s_cbranch_execz .LBB0_660
	global_load_dwordx4 v[18:21], v[120:121], off
	global_load_dwordx4 v[22:25], v[122:123], off
	global_load_dwordx4 v[26:29], v[124:125], off
	global_load_dwordx4 v[30:33], v[126:127], off

.LBB0_663:
	ds_read_b32 v182, v140
	s_waitcnt vmcnt(3)
	v_and_b32_e32 v199, 0xffff0000, v78
	v_lshlrev_b32_e32 v198, 16, v78
	s_waitcnt vmcnt(2)
	v_and_b32_e32 v231, 0xffff0000, v74
	v_and_b32_e32 v230, 0xffff0000, v80
	s_waitcnt lgkmcnt(0)
	v_sub_f32_e32 v82, v181, v182
	v_mul_f32_e32 v183, 0x3fb8aa3b, v82
	ds_read_b128 v[82:85], v152
	ds_read_b128 v[86:89], v152 offset:1088
	ds_read_b128 v[90:93], v152 offset:64
	ds_read_b128 v[94:97], v152 offset:1152
	v_readlane_b32 s16, v254, 25
	s_waitcnt lgkmcnt(3)
	v_mfma_f32_16x16x32_bf16 v[82:85], v[82:85], v[78:81], 0
	v_readlane_b32 s17, v254, 26
	v_lshlrev_b64 v[132:133], 10, v[132:133]
	s_mov_b32 s0, 0
	s_waitcnt lgkmcnt(2)
	v_mfma_f32_16x16x32_bf16 v[86:89], v[86:89], v[78:81], 0
	s_waitcnt lgkmcnt(1)
	v_mfma_f32_16x16x32_bf16 v[82:85], v[90:93], v[74:77], v[82:85]
	s_waitcnt lgkmcnt(0)
	v_mfma_f32_16x16x32_bf16 v[86:89], v[94:97], v[74:77], v[86:89]
	ds_read_b128 v[90:93], v152 offset:128
	ds_read_b128 v[94:97], v152 offset:1216
	s_waitcnt vmcnt(1) lgkmcnt(1)
	v_mfma_f32_16x16x32_bf16 v[82:85], v[90:93], v[70:73], v[82:85]
	s_waitcnt lgkmcnt(0)
	v_mfma_f32_16x16x32_bf16 v[86:89], v[94:97], v[70:73], v[86:89]
	ds_read_b128 v[90:93], v152 offset:192
	ds_read_b128 v[94:97], v152 offset:1280
	s_waitcnt vmcnt(0) lgkmcnt(1)
	v_mfma_f32_16x16x32_bf16 v[82:85], v[90:93], v[66:69], v[82:85]
	s_waitcnt lgkmcnt(0)
	v_mfma_f32_16x16x32_bf16 v[86:89], v[94:97], v[66:69], v[86:89]
	ds_read_b128 v[90:93], v142
	ds_read_b128 v[94:97], v142 offset:16
	s_waitcnt lgkmcnt(1)
	v_sub_f32_e32 v90, v90, v182
	v_sub_f32_e32 v91, v91, v182
	v_mul_f32_e32 v90, 0x3fb8aa3b, v90
	v_mul_f32_e32 v91, 0x3fb8aa3b, v91
	v_exp_f32_e32 v90, v90
	v_exp_f32_e32 v91, v91
	v_mul_f32_e32 v82, v82, v90
	v_mul_f32_e32 v83, v83, v91
	v_cndmask_b32_e64 v90, v82, 0, s[24:25]
	s_waitcnt lgkmcnt(0)
	v_sub_f32_e32 v82, v94, v182
	v_cndmask_b32_e64 v91, 0, v83, s[26:27]
	v_sub_f32_e32 v83, v95, v182
	v_mul_f32_e32 v82, 0x3fb8aa3b, v82
	v_mul_f32_e32 v83, 0x3fb8aa3b, v83
	v_exp_f32_e32 v82, v82
	v_exp_f32_e32 v83, v83
	s_nop 0
	v_pk_mul_f32 v[82:83], v[86:87], v[82:83]
	s_nop 0
	v_cndmask_b32_e64 v95, v83, 0, s[28:29]
	v_sub_f32_e32 v83, v96, v182
	v_mul_f32_e32 v83, 0x3fb8aa3b, v83
	v_cndmask_b32_e64 v98, v82, 0, s[30:31]
	v_sub_f32_e32 v82, v92, v182
	v_exp_f32_e32 v86, v83
	v_sub_f32_e32 v83, v93, v182
	v_mul_f32_e32 v82, 0x3fb8aa3b, v82
	v_mul_f32_e32 v83, 0x3fb8aa3b, v83
	v_exp_f32_e32 v82, v82
	v_exp_f32_e32 v83, v83
	s_nop 0
	v_pk_mul_f32 v[82:83], v[84:85], v[82:83]
	s_nop 0
	v_cndmask_b32_e64 v85, v82, 0, s[36:37]
	v_sub_f32_e32 v82, v97, v182
	v_mul_f32_e32 v82, 0x3fb8aa3b, v82
	v_exp_f32_e32 v87, v82
	v_cndmask_b32_e64 v84, v83, 0, s[34:35]
	v_pk_mul_f32 v[82:83], v[88:89], v[86:87]
	s_nop 0
	v_cndmask_b32_e64 v87, v82, 0, s[40:41]
	v_add_f32_e32 v82, 0, v90
	v_add_f32_e32 v82, v91, v82
	v_add_f32_e32 v82, v85, v82
	v_add_f32_e32 v82, v84, v82
	v_add_f32_e32 v82, v98, v82
	v_add_f32_e32 v82, v95, v82
	v_cndmask_b32_e64 v86, v83, 0, s[38:39]
	v_add_f32_e32 v82, v87, v82
	v_add_f32_e32 v94, v86, v82
	v_cvt_pk_bf16_f32 v82, v90, v91
	v_cvt_pk_bf16_f32 v83, v85, v84
	v_cvt_pk_bf16_f32 v85, v87, v86
	ds_read_b128 v[86:89], v152 offset:8704
	ds_read_b128 v[90:93], v152 offset:9792
	v_cvt_pk_bf16_f32 v84, v98, v95
	ds_read_b128 v[96:99], v152 offset:8768
	ds_read_b128 v[184:187], v152 offset:9856
	s_waitcnt lgkmcnt(3)
	v_mfma_f32_16x16x32_bf16 v[86:89], v[86:89], v[78:81], 0
	s_waitcnt lgkmcnt(2)
	v_mfma_f32_16x16x32_bf16 v[90:93], v[90:93], v[78:81], 0
	s_waitcnt lgkmcnt(1)
	v_mfma_f32_16x16x32_bf16 v[86:89], v[96:99], v[74:77], v[86:89]
	s_waitcnt lgkmcnt(0)
	v_mfma_f32_16x16x32_bf16 v[90:93], v[184:187], v[74:77], v[90:93]
	ds_read_b128 v[96:99], v152 offset:8832
	ds_read_b128 v[184:187], v152 offset:9920
	s_waitcnt lgkmcnt(1)
	v_mfma_f32_16x16x32_bf16 v[86:89], v[96:99], v[70:73], v[86:89]
	s_waitcnt lgkmcnt(0)
	v_mfma_f32_16x16x32_bf16 v[96:99], v[184:187], v[70:73], v[90:93]
	s_nop 2
	ds_read_b128 v[90:93], v152 offset:8896
	ds_read_b128 v[184:187], v152 offset:9984
	s_waitcnt lgkmcnt(1)
	v_mfma_f32_16x16x32_bf16 v[90:93], v[90:93], v[66:69], v[86:89]
	s_waitcnt lgkmcnt(0)
	v_mfma_f32_16x16x32_bf16 v[86:89], v[184:187], v[66:69], v[96:99]
	s_nop 2
	ds_read_b128 v[96:99], v142 offset:128
	ds_read_b128 v[184:187], v142 offset:144
	s_waitcnt lgkmcnt(1)
	v_sub_f32_e32 v95, v96, v182
	v_mul_f32_e32 v95, 0x3fb8aa3b, v95
	v_exp_f32_e32 v96, v95
	s_waitcnt lgkmcnt(0)
	v_sub_f32_e32 v95, v184, v182
	v_mul_f32_e32 v95, 0x3fb8aa3b, v95
	v_exp_f32_e32 v100, v95
	v_sub_f32_e32 v95, v97, v182
	v_mul_f32_e32 v95, 0x3fb8aa3b, v95
	v_exp_f32_e32 v97, v95
	s_nop 0
	v_pk_mul_f32 v[90:91], v[90:91], v[96:97]
	s_nop 0
	v_cndmask_b32_e64 v96, v90, 0, s[44:45]
	v_sub_f32_e32 v90, v185, v182
	v_mul_f32_e32 v90, 0x3fb8aa3b, v90
	v_exp_f32_e32 v101, v90
	v_cndmask_b32_e64 v95, v91, 0, s[42:43]
	v_pk_mul_f32 v[86:87], v[86:87], v[100:101]
	s_nop 0
	v_cndmask_b32_e64 v97, v87, 0, s[46:47]
	v_sub_f32_e32 v87, v186, v182
	v_mul_f32_e32 v87, 0x3fb8aa3b, v87
	v_cndmask_b32_e64 v100, v86, 0, s[48:49]
	v_sub_f32_e32 v86, v98, v182
	v_exp_f32_e32 v90, v87
	v_sub_f32_e32 v87, v99, v182
	v_mul_f32_e32 v86, 0x3fb8aa3b, v86
	v_mul_f32_e32 v87, 0x3fb8aa3b, v87
	v_exp_f32_e32 v86, v86
	v_exp_f32_e32 v87, v87
	s_nop 0
	v_pk_mul_f32 v[86:87], v[92:93], v[86:87]
	s_nop 0
	v_cndmask_b32_e64 v93, v86, 0, s[52:53]
	v_sub_f32_e32 v86, v187, v182
	v_mul_f32_e32 v86, 0x3fb8aa3b, v86
	v_exp_f32_e32 v91, v86
	v_cndmask_b32_e64 v92, v87, 0, s[50:51]
	v_pk_mul_f32 v[86:87], v[88:89], v[90:91]
	s_nop 0
	v_cndmask_b32_e64 v90, v86, 0, s[56:57]
	v_add_f32_e32 v86, v94, v96
	v_add_f32_e32 v86, v95, v86
	v_add_f32_e32 v86, v93, v86
	v_add_f32_e32 v86, v92, v86
	v_add_f32_e32 v86, v100, v86
	v_add_f32_e32 v86, v97, v86
	v_cndmask_b32_e64 v89, v87, 0, s[54:55]
	v_add_f32_e32 v86, v90, v86
	v_add_f32_e32 v98, v89, v86
	v_cvt_pk_bf16_f32 v86, v96, v95
	v_cvt_pk_bf16_f32 v87, v93, v92
	v_cvt_pk_bf16_f32 v88, v100, v97
	v_cvt_pk_bf16_f32 v89, v90, v89
	ds_read_b128 v[90:93], v152 offset:17408
	ds_read_b128 v[94:97], v152 offset:18496
	ds_read_b128 v[184:187], v152 offset:17472
	ds_read_b128 v[188:191], v152 offset:18560
	s_waitcnt lgkmcnt(3)
	v_mfma_f32_16x16x32_bf16 v[90:93], v[90:93], v[78:81], 0
	s_waitcnt lgkmcnt(2)
	v_mfma_f32_16x16x32_bf16 v[94:97], v[94:97], v[78:81], 0
	s_waitcnt lgkmcnt(1)
	v_mfma_f32_16x16x32_bf16 v[90:93], v[184:187], v[74:77], v[90:93]
	s_waitcnt lgkmcnt(0)
	v_mfma_f32_16x16x32_bf16 v[94:97], v[188:191], v[74:77], v[94:97]
	ds_read_b128 v[184:187], v152 offset:17536
	ds_read_b128 v[188:191], v152 offset:18624
	s_waitcnt lgkmcnt(1)
	v_mfma_f32_16x16x32_bf16 v[90:93], v[184:187], v[70:73], v[90:93]
	s_waitcnt lgkmcnt(0)
	v_mfma_f32_16x16x32_bf16 v[184:187], v[188:191], v[70:73], v[94:97]
	s_nop 2
	ds_read_b128 v[94:97], v152 offset:17600
	ds_read_b128 v[188:191], v152 offset:18688
	s_waitcnt lgkmcnt(1)
	v_mfma_f32_16x16x32_bf16 v[94:97], v[94:97], v[66:69], v[90:93]
	s_waitcnt lgkmcnt(0)
	v_mfma_f32_16x16x32_bf16 v[90:93], v[188:191], v[66:69], v[184:187]
	s_nop 2
	ds_read_b128 v[184:187], v142 offset:256
	ds_read_b128 v[188:191], v142 offset:272
	s_waitcnt lgkmcnt(1)
	v_sub_f32_e32 v99, v184, v182
	v_mul_f32_e32 v99, 0x3fb8aa3b, v99
	v_exp_f32_e32 v100, v99
	s_waitcnt lgkmcnt(0)
	v_sub_f32_e32 v99, v188, v182
	v_mul_f32_e32 v99, 0x3fb8aa3b, v99
	v_exp_f32_e32 v184, v99
	v_sub_f32_e32 v99, v185, v182
	v_mul_f32_e32 v99, 0x3fb8aa3b, v99
	v_exp_f32_e32 v101, v99
	s_nop 0
	v_pk_mul_f32 v[94:95], v[94:95], v[100:101]
	s_nop 0
	v_cndmask_b32_e64 v100, v94, 0, s[60:61]
	v_sub_f32_e32 v94, v189, v182
	v_mul_f32_e32 v94, 0x3fb8aa3b, v94
	v_exp_f32_e32 v185, v94
	v_cndmask_b32_e64 v99, v95, 0, s[58:59]
	v_pk_mul_f32 v[90:91], v[90:91], v[184:185]
	s_nop 0
	v_cndmask_b32_e64 v101, v91, 0, s[62:63]
	v_sub_f32_e32 v91, v190, v182
	v_mul_f32_e32 v91, 0x3fb8aa3b, v91
	v_cndmask_b32_e64 v172, v90, 0, s[64:65]
	v_sub_f32_e32 v90, v186, v182
	v_exp_f32_e32 v94, v91
	v_sub_f32_e32 v91, v187, v182
	v_mul_f32_e32 v90, 0x3fb8aa3b, v90
	v_mul_f32_e32 v91, 0x3fb8aa3b, v91
	v_exp_f32_e32 v90, v90
	v_exp_f32_e32 v91, v91
	s_nop 0
	v_pk_mul_f32 v[90:91], v[96:97], v[90:91]
	s_nop 0
	v_cndmask_b32_e64 v97, v90, 0, s[68:69]
	v_sub_f32_e32 v90, v191, v182
	v_mul_f32_e32 v90, 0x3fb8aa3b, v90
	v_exp_f32_e32 v95, v90
	v_cndmask_b32_e64 v96, v91, 0, s[66:67]
	v_pk_mul_f32 v[90:91], v[92:93], v[94:95]
	s_nop 0
	v_cndmask_b32_e64 v94, v90, 0, s[72:73]
	v_add_f32_e32 v90, v98, v100
	v_add_f32_e32 v90, v99, v90
	v_add_f32_e32 v90, v97, v90
	v_add_f32_e32 v90, v96, v90
	v_add_f32_e32 v90, v172, v90
	v_add_f32_e32 v90, v101, v90
	v_cndmask_b32_e64 v93, v91, 0, s[70:71]
	v_add_f32_e32 v90, v94, v90
	v_add_f32_e32 v184, v93, v90
	v_cvt_pk_bf16_f32 v90, v100, v99
	v_cvt_pk_bf16_f32 v91, v97, v96
	v_cvt_pk_bf16_f32 v92, v172, v101
	v_cvt_pk_bf16_f32 v93, v94, v93
	ds_read_b128 v[94:97], v152 offset:26112
	ds_read_b128 v[98:101], v152 offset:27200
	ds_read_b128 v[186:189], v152 offset:26176
	ds_read_b128 v[190:193], v152 offset:27264
	s_waitcnt lgkmcnt(3)
	v_mfma_f32_16x16x32_bf16 v[94:97], v[94:97], v[78:81], 0
	s_waitcnt lgkmcnt(2)
	v_mfma_f32_16x16x32_bf16 v[98:101], v[98:101], v[78:81], 0
	s_waitcnt lgkmcnt(1)
	v_mfma_f32_16x16x32_bf16 v[94:97], v[186:189], v[74:77], v[94:97]
	s_waitcnt lgkmcnt(0)
	v_mfma_f32_16x16x32_bf16 v[98:101], v[190:193], v[74:77], v[98:101]
	ds_read_b128 v[186:189], v152 offset:26240
	ds_read_b128 v[190:193], v152 offset:27328
	s_waitcnt lgkmcnt(1)
	v_mfma_f32_16x16x32_bf16 v[94:97], v[186:189], v[70:73], v[94:97]
	s_waitcnt lgkmcnt(0)
	v_mfma_f32_16x16x32_bf16 v[186:189], v[190:193], v[70:73], v[98:101]
	s_nop 2
	ds_read_b128 v[98:101], v152 offset:26304
	ds_read_b128 v[190:193], v152 offset:27392
	s_waitcnt lgkmcnt(1)
	v_mfma_f32_16x16x32_bf16 v[98:101], v[98:101], v[66:69], v[94:97]
	s_waitcnt lgkmcnt(0)
	v_mfma_f32_16x16x32_bf16 v[94:97], v[190:193], v[66:69], v[186:189]
	s_nop 2
	ds_read_b128 v[186:189], v142 offset:384
	ds_read_b128 v[190:193], v142 offset:400
	s_waitcnt lgkmcnt(1)
	v_sub_f32_e32 v172, v186, v182
	v_mul_f32_e32 v172, 0x3fb8aa3b, v172
	v_exp_f32_e32 v186, v172
	s_waitcnt lgkmcnt(0)
	v_sub_f32_e32 v172, v190, v182
	v_mul_f32_e32 v172, 0x3fb8aa3b, v172
	v_exp_f32_e32 v190, v172
	v_sub_f32_e32 v172, v187, v182
	v_mul_f32_e32 v172, 0x3fb8aa3b, v172
	v_exp_f32_e32 v187, v172
	s_nop 0
	v_pk_mul_f32 v[98:99], v[98:99], v[186:187]
	s_nop 0
	v_cndmask_b32_e64 v173, v98, 0, s[76:77]
	v_sub_f32_e32 v98, v191, v182
	v_mul_f32_e32 v98, 0x3fb8aa3b, v98
	v_exp_f32_e32 v191, v98
	v_cndmask_b32_e64 v172, v99, 0, s[74:75]
	v_pk_mul_f32 v[94:95], v[94:95], v[190:191]
	s_nop 0
	v_cndmask_b32_e64 v190, v95, 0, s[78:79]
	v_sub_f32_e32 v95, v192, v182
	v_mul_f32_e32 v95, 0x3fb8aa3b, v95
	v_cndmask_b32_e64 v194, v94, 0, s[80:81]
	v_sub_f32_e32 v94, v188, v182
	v_exp_f32_e32 v98, v95
	v_sub_f32_e32 v95, v189, v182
	v_mul_f32_e32 v94, 0x3fb8aa3b, v94
	v_mul_f32_e32 v95, 0x3fb8aa3b, v95
	v_exp_f32_e32 v94, v94
	v_exp_f32_e32 v95, v95
	s_nop 0
	v_pk_mul_f32 v[94:95], v[100:101], v[94:95]
	s_nop 0
	v_cndmask_b32_e64 v101, v94, 0, s[84:85]
	v_sub_f32_e32 v94, v193, v182
	v_mul_f32_e32 v94, 0x3fb8aa3b, v94
	v_exp_f32_e32 v99, v94
	v_cndmask_b32_e64 v100, v95, 0, s[82:83]
	v_pk_mul_f32 v[94:95], v[96:97], v[98:99]
	s_nop 0
	v_cndmask_b32_e64 v192, v94, 0, s[88:89]
	v_add_f32_e32 v94, v184, v173
	v_add_f32_e32 v94, v172, v94
	v_add_f32_e32 v94, v101, v94
	v_add_u32_e32 v98, 0, v141
	v_add_f32_e32 v196, v100, v94
	v_cvt_pk_bf16_f32 v94, v173, v172
	v_add_u32_e32 v172, 0x22600, v98
	v_cndmask_b32_e64 v188, v95, 0, s[86:87]
	v_cvt_pk_bf16_f32 v95, v101, v100
	ds_read_b128 v[98:101], v172
	ds_read_b128 v[184:187], v172 offset:16
	v_cvt_pk_bf16_f32 v97, v192, v188
	v_cvt_pk_bf16_f32 v96, v194, v190
	s_waitcnt lgkmcnt(1)
	v_pk_mul_f32 v[98:99], v[98:99], v[198:199]
	v_and_b32_e32 v199, 0xffff0000, v79
	v_lshlrev_b32_e32 v198, 16, v79
	v_pk_mul_f32 v[100:101], v[100:101], v[198:199]
	v_add_f32_e32 v98, v98, v99
	v_add_f32_e32 v98, v100, v98
	v_add_f32_e32 v98, v101, v98
	v_add_f32_e32 v173, 0, v98
	ds_read_b128 v[98:101], v172 offset:128
	v_lshlrev_b32_e32 v199, 16, v74
	v_lshlrev_b32_e32 v198, 16, v80
	s_waitcnt lgkmcnt(1)
	v_mov_b32_e32 v200, v184
	v_lshlrev_b32_e32 v184, 16, v81
	s_waitcnt lgkmcnt(0)
	v_mov_b32_e32 v201, v98
	v_mov_b32_e32 v98, v185
	v_pk_mul_f32 v[98:99], v[98:99], v[230:231]
	v_lshlrev_b32_e32 v185, 16, v75
	v_pk_fma_f32 v[98:99], v[200:201], v[198:199], v[98:99]
	v_mov_b32_e32 v198, v186
	v_mov_b32_e32 v199, v100
	v_pk_fma_f32 v[98:99], v[198:199], v[184:185], v[98:99]
	v_and_b32_e32 v185, 0xffff0000, v75
	v_and_b32_e32 v184, 0xffff0000, v81
	v_mov_b32_e32 v100, v187
	v_pk_fma_f32 v[98:99], v[100:101], v[184:185], v[98:99]
	v_and_b32_e32 v231, 0xffff0000, v70
	v_add_f32_e32 v98, v173, v98
	v_add_f32_e32 v173, v98, v99
	ds_read_b128 v[98:101], v172 offset:144
	ds_read_b128 v[184:187], v172 offset:256
	v_and_b32_e32 v230, 0xffff0000, v76
	v_lshlrev_b32_e32 v199, 16, v70
	v_lshlrev_b32_e32 v198, 16, v76
	s_waitcnt lgkmcnt(1)
	v_mov_b32_e32 v200, v98
	s_waitcnt lgkmcnt(0)
	v_mov_b32_e32 v201, v184
	v_mov_b32_e32 v184, v99
	v_pk_mul_f32 v[98:99], v[184:185], v[230:231]
	v_lshlrev_b32_e32 v185, 16, v71
	v_pk_fma_f32 v[98:99], v[200:201], v[198:199], v[98:99]
	v_lshlrev_b32_e32 v184, 16, v77
	v_mov_b32_e32 v198, v100
	v_mov_b32_e32 v199, v186
	v_pk_fma_f32 v[98:99], v[198:199], v[184:185], v[98:99]
	v_and_b32_e32 v185, 0xffff0000, v71
	v_and_b32_e32 v184, 0xffff0000, v77
	v_mov_b32_e32 v186, v101
	v_pk_fma_f32 v[98:99], v[186:187], v[184:185], v[98:99]
	v_and_b32_e32 v231, 0xffff0000, v66
	v_add_f32_e32 v98, v173, v98
	v_add_f32_e32 v173, v98, v99
	ds_read_b128 v[98:101], v172 offset:272
	ds_read_b128 v[184:187], v172 offset:384
	v_and_b32_e32 v230, 0xffff0000, v72
	v_lshlrev_b32_e32 v199, 16, v66
	v_lshlrev_b32_e32 v198, 16, v72
	s_waitcnt lgkmcnt(1)
	v_mov_b32_e32 v200, v98
	s_waitcnt lgkmcnt(0)
	v_mov_b32_e32 v201, v184
	v_mov_b32_e32 v184, v99
	v_pk_mul_f32 v[98:99], v[184:185], v[230:231]
	v_lshlrev_b32_e32 v185, 16, v67
	v_pk_fma_f32 v[98:99], v[200:201], v[198:199], v[98:99]
	v_lshlrev_b32_e32 v184, 16, v73
	v_mov_b32_e32 v198, v100
	v_mov_b32_e32 v199, v186
	v_pk_fma_f32 v[98:99], v[198:199], v[184:185], v[98:99]
	v_and_b32_e32 v185, 0xffff0000, v67
	v_and_b32_e32 v184, 0xffff0000, v73
	v_mov_b32_e32 v186, v101
	v_pk_fma_f32 v[98:99], v[186:187], v[184:185], v[98:99]
	s_load_dwordx2 s[16:17], s[16:17], 0x118
	v_add_f32_e32 v98, v173, v98
	v_add_f32_e32 v189, v98, v99
	ds_read_b128 v[98:101], v172 offset:400
	v_lshlrev_b32_e32 v172, 16, v68
	s_waitcnt lgkmcnt(0)
	v_lshl_add_u64 v[134:135], s[16:17], 0, v[134:135]
	s_mov_b64 s[16:17], 0x2134200
	v_lshl_add_u64 v[134:135], v[134:135], 0, s[16:17]
	v_mul_f32_e32 v195, v98, v172
	v_and_b32_e32 v98, 0xffff0000, v68
	v_mul_f32_e32 v197, v99, v98
	v_lshlrev_b32_e32 v98, 16, v69
	v_mul_f32_e32 v191, v100, v98
	v_and_b32_e32 v98, 0xffff0000, v69
	v_mul_f32_e32 v193, v101, v98
	v_pk_add_f32 v[100:101], v[194:195], v[196:197]
	ds_read_b32 v99, v145
	v_pk_add_f32 v[100:101], v[190:191], v[100:101]
	v_exp_f32_e32 v98, v183
	v_pk_add_f32 v[100:101], v[192:193], v[100:101]
	v_readlane_b32 s16, v254, 60
	v_pk_add_f32 v[100:101], v[188:189], v[100:101]
	ds_bpermute_b32 v184, v143, v100
	ds_bpermute_b32 v185, v143, v101
	ds_read_b128 v[186:189], v169 offset:64
	s_waitcnt lgkmcnt(3)
	v_add_f32_e32 v99, v182, v99
	v_mul_f32_e32 v99, 0xbfb8aa3b, v99
	v_exp_f32_e32 v99, v99
	s_waitcnt lgkmcnt(1)
	v_pk_add_f32 v[100:101], v[100:101], v[184:185]
	ds_bpermute_b32 v184, v144, v100
	ds_bpermute_b32 v185, v144, v101
	v_readlane_b32 s17, v254, 61
	s_waitcnt lgkmcnt(0)
	v_pk_add_f32 v[100:101], v[100:101], v[184:185]
	ds_read_b128 v[182:185], v169
	s_waitcnt lgkmcnt(0)
	v_mfma_f32_16x16x32_bf16 v[182:185], v[182:185], v[78:81], 0
	v_fmac_f32_e32 v100, v98, v101
	v_max_f32_e64 v99, |v100|, v99
	v_div_scale_f32 v100, s[90:91], v99, v99, 1.0
	v_mfma_f32_16x16x32_bf16 v[182:185], v[186:189], v[74:77], v[182:185]
	ds_read_b128 v[186:189], v169 offset:128
	v_rcp_f32_e32 v101, v100
	v_lshl_add_u64 v[132:133], s[16:17], 0, v[132:133]
	s_waitcnt lgkmcnt(0)
	v_mfma_f32_16x16x32_bf16 v[182:185], v[186:189], v[70:73], v[182:185]
	ds_read_b128 v[186:189], v169 offset:192
	v_fma_f32 v172, -v100, v101, 1.0
	v_fmac_f32_e32 v101, v172, v101
	s_waitcnt lgkmcnt(0)
	v_mfma_f32_16x16x32_bf16 v[182:185], v[186:189], v[66:69], v[182:185]
	ds_read_b128 v[186:189], v176
	v_div_scale_f32 v172, vcc, 1.0, v99, 1.0
	s_nop 5
	v_pk_mul_f32 v[184:185], v[98:99], v[184:185] op_sel_hi:[0,1]
	v_pk_mul_f32 v[182:183], v[98:99], v[182:183] op_sel_hi:[0,1]
	v_mul_f32_e32 v173, v172, v101
	v_fma_f32 v174, -v100, v173, v172
	s_waitcnt lgkmcnt(0)
	v_mfma_f32_16x16x32_bf16 v[182:185], v[186:189], v[82:85], v[182:185]
	ds_read_b128 v[186:189], v176 offset:64
	v_fmac_f32_e32 v173, v174, v101
	v_fma_f32 v100, -v100, v173, v172
	s_waitcnt lgkmcnt(0)
	v_mfma_f32_16x16x32_bf16 v[182:185], v[186:189], v[86:89], v[182:185]
	ds_read_b128 v[186:189], v176 offset:128
	v_div_fmas_f32 v100, v100, v101, v173
	v_readlane_b32 s90, v254, 19
	s_waitcnt lgkmcnt(0)
	v_mfma_f32_16x16x32_bf16 v[182:185], v[186:189], v[90:93], v[182:185]
	ds_read_b128 v[186:189], v176 offset:192
	v_div_fixup_f32 v100, v100, v99, 1.0
	v_cndmask_b32_e64 v133, v133, v135, s[6:7]
	s_waitcnt lgkmcnt(0)
	v_mfma_f32_16x16x32_bf16 v[182:185], v[186:189], v[94:97], v[182:185]
	v_cndmask_b32_e64 v132, v132, v134, s[6:7]
	v_readlane_b32 s91, v254, 20
	ds_read_b128 v[186:189], v169 offset:4416
	s_nop 4
	v_pk_mul_f32 v[134:135], v[100:101], v[184:185] op_sel_hi:[0,1]
	v_lshl_add_u64 v[132:133], v[132:133], 0, s[90:91]
	v_pk_mul_f32 v[182:183], v[100:101], v[182:183] op_sel_hi:[0,1]
	v_lshl_add_u64 v[132:133], v[132:133], 0, v[0:1]
	v_cvt_pk_bf16_f32 v182, v182, v183
	v_cvt_pk_bf16_f32 v183, v134, v135
	global_store_dwordx2 v[132:133], v[182:183], off
	ds_read_b128 v[182:185], v169 offset:4352
	s_waitcnt lgkmcnt(0)
	v_mfma_f32_16x16x32_bf16 v[182:185], v[182:185], v[78:81], 0
	v_mfma_f32_16x16x32_bf16 v[182:185], v[186:189], v[74:77], v[182:185]
	ds_read_b128 v[186:189], v169 offset:4480
	s_waitcnt lgkmcnt(0)
	v_mfma_f32_16x16x32_bf16 v[182:185], v[186:189], v[70:73], v[182:185]
	ds_read_b128 v[186:189], v169 offset:4544
	s_waitcnt lgkmcnt(0)
	v_mfma_f32_16x16x32_bf16 v[182:185], v[186:189], v[66:69], v[182:185]
	ds_read_b128 v[186:189], v176 offset:4352
	s_nop 6
	v_pk_mul_f32 v[184:185], v[98:99], v[184:185] op_sel_hi:[0,1]
	v_pk_mul_f32 v[182:183], v[98:99], v[182:183] op_sel_hi:[0,1]
	s_waitcnt lgkmcnt(0)
	s_nop 0
	v_mfma_f32_16x16x32_bf16 v[182:185], v[186:189], v[82:85], v[182:185]
	ds_read_b128 v[186:189], v176 offset:4416
	s_waitcnt lgkmcnt(0)
	v_mfma_f32_16x16x32_bf16 v[182:185], v[186:189], v[86:89], v[182:185]
	ds_read_b128 v[186:189], v176 offset:4480
	s_waitcnt lgkmcnt(0)
	v_mfma_f32_16x16x32_bf16 v[182:185], v[186:189], v[90:93], v[182:185]
	ds_read_b128 v[186:189], v176 offset:4544
	s_waitcnt lgkmcnt(0)
	v_mfma_f32_16x16x32_bf16 v[182:185], v[186:189], v[94:97], v[182:185]
	ds_read_b128 v[186:189], v169 offset:8768
	s_nop 6
	v_pk_mul_f32 v[134:135], v[100:101], v[184:185] op_sel_hi:[0,1]
	v_pk_mul_f32 v[182:183], v[100:101], v[182:183] op_sel_hi:[0,1]
	v_cvt_pk_bf16_f32 v182, v182, v183
	v_cvt_pk_bf16_f32 v183, v134, v135
	global_store_dwordx2 v[132:133], v[182:183], off offset:32
	ds_read_b128 v[182:185], v169 offset:8704
	s_waitcnt lgkmcnt(0)
	v_mfma_f32_16x16x32_bf16 v[182:185], v[182:185], v[78:81], 0
	v_mfma_f32_16x16x32_bf16 v[182:185], v[186:189], v[74:77], v[182:185]
	ds_read_b128 v[186:189], v169 offset:8832
	s_waitcnt lgkmcnt(0)
	v_mfma_f32_16x16x32_bf16 v[182:185], v[186:189], v[70:73], v[182:185]
	ds_read_b128 v[186:189], v169 offset:8896
	s_waitcnt lgkmcnt(0)
	v_mfma_f32_16x16x32_bf16 v[182:185], v[186:189], v[66:69], v[182:185]
	ds_read_b128 v[186:189], v176 offset:8704
	s_nop 6
	v_pk_mul_f32 v[184:185], v[98:99], v[184:185] op_sel_hi:[0,1]
	v_pk_mul_f32 v[182:183], v[98:99], v[182:183] op_sel_hi:[0,1]
	s_waitcnt lgkmcnt(0)
	s_nop 0
	v_mfma_f32_16x16x32_bf16 v[182:185], v[186:189], v[82:85], v[182:185]
	ds_read_b128 v[186:189], v176 offset:8768
	s_waitcnt lgkmcnt(0)
	v_mfma_f32_16x16x32_bf16 v[182:185], v[186:189], v[86:89], v[182:185]
	ds_read_b128 v[186:189], v176 offset:8832
	s_waitcnt lgkmcnt(0)
	v_mfma_f32_16x16x32_bf16 v[182:185], v[186:189], v[90:93], v[182:185]
	ds_read_b128 v[186:189], v176 offset:8896
	s_waitcnt lgkmcnt(0)
	v_mfma_f32_16x16x32_bf16 v[182:185], v[186:189], v[94:97], v[182:185]
	ds_read_b128 v[186:189], v169 offset:13120
	s_nop 6
	v_pk_mul_f32 v[134:135], v[100:101], v[184:185] op_sel_hi:[0,1]
	v_pk_mul_f32 v[182:183], v[100:101], v[182:183] op_sel_hi:[0,1]
	v_cvt_pk_bf16_f32 v182, v182, v183
	v_cvt_pk_bf16_f32 v183, v134, v135
	global_store_dwordx2 v[132:133], v[182:183], off offset:64
	ds_read_b128 v[182:185], v169 offset:13056
	s_waitcnt lgkmcnt(0)
	v_mfma_f32_16x16x32_bf16 v[182:185], v[182:185], v[78:81], 0
	v_mfma_f32_16x16x32_bf16 v[182:185], v[186:189], v[74:77], v[182:185]
	ds_read_b128 v[186:189], v169 offset:13184
	s_waitcnt lgkmcnt(0)
	v_mfma_f32_16x16x32_bf16 v[182:185], v[186:189], v[70:73], v[182:185]
	ds_read_b128 v[186:189], v169 offset:13248
	s_waitcnt lgkmcnt(0)
	v_mfma_f32_16x16x32_bf16 v[182:185], v[186:189], v[66:69], v[182:185]
	ds_read_b128 v[186:189], v176 offset:13056
	s_nop 6
	v_pk_mul_f32 v[184:185], v[98:99], v[184:185] op_sel_hi:[0,1]
	v_pk_mul_f32 v[182:183], v[98:99], v[182:183] op_sel_hi:[0,1]
	s_waitcnt lgkmcnt(0)
	s_nop 0
	v_mfma_f32_16x16x32_bf16 v[182:185], v[186:189], v[82:85], v[182:185]
	ds_read_b128 v[186:189], v176 offset:13120
	s_waitcnt lgkmcnt(0)
	v_mfma_f32_16x16x32_bf16 v[182:185], v[186:189], v[86:89], v[182:185]
	ds_read_b128 v[186:189], v176 offset:13184
	s_waitcnt lgkmcnt(0)
	v_mfma_f32_16x16x32_bf16 v[182:185], v[186:189], v[90:93], v[182:185]
	ds_read_b128 v[186:189], v176 offset:13248
	s_waitcnt lgkmcnt(0)
	v_mfma_f32_16x16x32_bf16 v[182:185], v[186:189], v[94:97], v[182:185]
	ds_read_b128 v[186:189], v169 offset:17472
	s_nop 6
	v_pk_mul_f32 v[134:135], v[100:101], v[184:185] op_sel_hi:[0,1]
	v_pk_mul_f32 v[182:183], v[100:101], v[182:183] op_sel_hi:[0,1]
	v_cvt_pk_bf16_f32 v182, v182, v183
	v_cvt_pk_bf16_f32 v183, v134, v135
	global_store_dwordx2 v[132:133], v[182:183], off offset:96
	ds_read_b128 v[182:185], v169 offset:17408
	s_waitcnt lgkmcnt(0)
	v_mfma_f32_16x16x32_bf16 v[182:185], v[182:185], v[78:81], 0
	v_mfma_f32_16x16x32_bf16 v[182:185], v[186:189], v[74:77], v[182:185]
	ds_read_b128 v[186:189], v169 offset:17536
	s_waitcnt lgkmcnt(0)
	v_mfma_f32_16x16x32_bf16 v[182:185], v[186:189], v[70:73], v[182:185]
	ds_read_b128 v[186:189], v169 offset:17600
	s_waitcnt lgkmcnt(0)
	v_mfma_f32_16x16x32_bf16 v[182:185], v[186:189], v[66:69], v[182:185]
	ds_read_b128 v[186:189], v176 offset:17408
	s_nop 6
	v_pk_mul_f32 v[184:185], v[98:99], v[184:185] op_sel_hi:[0,1]
	v_pk_mul_f32 v[182:183], v[98:99], v[182:183] op_sel_hi:[0,1]
	s_waitcnt lgkmcnt(0)
	s_nop 0
	v_mfma_f32_16x16x32_bf16 v[182:185], v[186:189], v[82:85], v[182:185]
	ds_read_b128 v[186:189], v176 offset:17472
	s_waitcnt lgkmcnt(0)
	v_mfma_f32_16x16x32_bf16 v[182:185], v[186:189], v[86:89], v[182:185]
	ds_read_b128 v[186:189], v176 offset:17536
	s_waitcnt lgkmcnt(0)
	v_mfma_f32_16x16x32_bf16 v[182:185], v[186:189], v[90:93], v[182:185]
	ds_read_b128 v[186:189], v176 offset:17600
	s_waitcnt lgkmcnt(0)
	v_mfma_f32_16x16x32_bf16 v[182:185], v[186:189], v[94:97], v[182:185]
	ds_read_b128 v[186:189], v169 offset:21824
	s_nop 6
	v_pk_mul_f32 v[134:135], v[100:101], v[184:185] op_sel_hi:[0,1]
	v_pk_mul_f32 v[182:183], v[100:101], v[182:183] op_sel_hi:[0,1]
	v_cvt_pk_bf16_f32 v182, v182, v183
	v_cvt_pk_bf16_f32 v183, v134, v135
	global_store_dwordx2 v[132:133], v[182:183], off offset:128
	ds_read_b128 v[182:185], v169 offset:21760
	s_waitcnt lgkmcnt(0)
	v_mfma_f32_16x16x32_bf16 v[182:185], v[182:185], v[78:81], 0
	v_mfma_f32_16x16x32_bf16 v[182:185], v[186:189], v[74:77], v[182:185]
	ds_read_b128 v[186:189], v169 offset:21888
	s_waitcnt lgkmcnt(0)
	v_mfma_f32_16x16x32_bf16 v[182:185], v[186:189], v[70:73], v[182:185]
	ds_read_b128 v[186:189], v169 offset:21952
	s_waitcnt lgkmcnt(0)
	v_mfma_f32_16x16x32_bf16 v[182:185], v[186:189], v[66:69], v[182:185]
	ds_read_b128 v[186:189], v176 offset:21760
	s_nop 6
	v_pk_mul_f32 v[184:185], v[98:99], v[184:185] op_sel_hi:[0,1]
	v_pk_mul_f32 v[182:183], v[98:99], v[182:183] op_sel_hi:[0,1]
	s_waitcnt lgkmcnt(0)
	s_nop 0
	v_mfma_f32_16x16x32_bf16 v[182:185], v[186:189], v[82:85], v[182:185]
	ds_read_b128 v[186:189], v176 offset:21824
	s_waitcnt lgkmcnt(0)
	v_mfma_f32_16x16x32_bf16 v[182:185], v[186:189], v[86:89], v[182:185]
	ds_read_b128 v[186:189], v176 offset:21888
	s_waitcnt lgkmcnt(0)
	v_mfma_f32_16x16x32_bf16 v[182:185], v[186:189], v[90:93], v[182:185]
	ds_read_b128 v[186:189], v176 offset:21952
	s_waitcnt lgkmcnt(0)
	v_mfma_f32_16x16x32_bf16 v[182:185], v[186:189], v[94:97], v[182:185]
	ds_read_b128 v[186:189], v169 offset:26176
	s_nop 6
	v_pk_mul_f32 v[134:135], v[100:101], v[184:185] op_sel_hi:[0,1]
	v_pk_mul_f32 v[182:183], v[100:101], v[182:183] op_sel_hi:[0,1]
	v_cvt_pk_bf16_f32 v182, v182, v183
	v_cvt_pk_bf16_f32 v183, v134, v135
	global_store_dwordx2 v[132:133], v[182:183], off offset:160
	ds_read_b128 v[182:185], v169 offset:26112
	s_waitcnt lgkmcnt(0)
	v_mfma_f32_16x16x32_bf16 v[182:185], v[182:185], v[78:81], 0
	v_mfma_f32_16x16x32_bf16 v[182:185], v[186:189], v[74:77], v[182:185]
	ds_read_b128 v[186:189], v169 offset:26240
	s_waitcnt lgkmcnt(0)
	v_mfma_f32_16x16x32_bf16 v[182:185], v[186:189], v[70:73], v[182:185]
	ds_read_b128 v[186:189], v169 offset:26304
	s_waitcnt lgkmcnt(0)
	v_mfma_f32_16x16x32_bf16 v[182:185], v[186:189], v[66:69], v[182:185]
	ds_read_b128 v[186:189], v176 offset:26112
	s_nop 6
	v_pk_mul_f32 v[184:185], v[98:99], v[184:185] op_sel_hi:[0,1]
	v_pk_mul_f32 v[182:183], v[98:99], v[182:183] op_sel_hi:[0,1]
	s_waitcnt lgkmcnt(0)
	s_nop 0
	v_mfma_f32_16x16x32_bf16 v[182:185], v[186:189], v[82:85], v[182:185]
	ds_read_b128 v[186:189], v176 offset:26176
	s_waitcnt lgkmcnt(0)
	v_mfma_f32_16x16x32_bf16 v[182:185], v[186:189], v[86:89], v[182:185]
	ds_read_b128 v[186:189], v176 offset:26240
	s_waitcnt lgkmcnt(0)
	v_mfma_f32_16x16x32_bf16 v[182:185], v[186:189], v[90:93], v[182:185]
	ds_read_b128 v[186:189], v176 offset:26304
	s_waitcnt lgkmcnt(0)
	v_mfma_f32_16x16x32_bf16 v[182:185], v[186:189], v[94:97], v[182:185]
	s_nop 7
	v_pk_mul_f32 v[134:135], v[100:101], v[184:185] op_sel_hi:[0,1]
	v_pk_mul_f32 v[182:183], v[100:101], v[182:183] op_sel_hi:[0,1]
	v_cvt_pk_bf16_f32 v182, v182, v183
	v_cvt_pk_bf16_f32 v183, v134, v135
	global_store_dwordx2 v[132:133], v[182:183], off offset:192
	ds_read_b128 v[182:185], v169 offset:30464
	s_waitcnt lgkmcnt(0)
	v_mfma_f32_16x16x32_bf16 v[78:81], v[182:185], v[78:81], 0
	ds_read_b128 v[182:185], v169 offset:30528
	s_waitcnt lgkmcnt(0)
	v_mfma_f32_16x16x32_bf16 v[74:77], v[182:185], v[74:77], v[78:81]
	s_nop 4
	ds_read_b128 v[78:81], v169 offset:30592
	s_waitcnt lgkmcnt(0)
	v_mfma_f32_16x16x32_bf16 v[70:73], v[78:81], v[70:73], v[74:77]
	s_nop 2
	ds_read_b128 v[74:77], v169 offset:30656
	s_waitcnt lgkmcnt(0)
	v_mfma_f32_16x16x32_bf16 v[66:69], v[74:77], v[66:69], v[70:73]
	s_nop 2
	ds_read_b128 v[70:73], v176 offset:30464
	s_nop 3
	v_pk_mul_f32 v[68:69], v[98:99], v[68:69] op_sel_hi:[0,1]
	v_pk_mul_f32 v[66:67], v[98:99], v[66:67] op_sel_hi:[0,1]
	s_waitcnt lgkmcnt(0)
	s_nop 0
	v_mfma_f32_16x16x32_bf16 v[66:69], v[70:73], v[82:85], v[66:69]
	ds_read_b128 v[70:73], v176 offset:30528
	s_waitcnt lgkmcnt(0)
	v_mfma_f32_16x16x32_bf16 v[66:69], v[70:73], v[86:89], v[66:69]
	ds_read_b128 v[70:73], v176 offset:30592
	s_waitcnt lgkmcnt(0)
	v_mfma_f32_16x16x32_bf16 v[66:69], v[70:73], v[90:93], v[66:69]
	ds_read_b128 v[70:73], v176 offset:30656
	s_waitcnt lgkmcnt(0)
	v_mfma_f32_16x16x32_bf16 v[66:69], v[70:73], v[94:97], v[66:69]
	s_nop 7
	v_pk_mul_f32 v[68:69], v[100:101], v[68:69] op_sel_hi:[0,1]
	v_pk_mul_f32 v[66:67], v[100:101], v[66:67] op_sel_hi:[0,1]
	v_cvt_pk_bf16_f32 v66, v66, v67
	v_cvt_pk_bf16_f32 v67, v68, v69
	global_store_dwordx2 v[132:133], v[66:67], off offset:224
	v_sub_f32_e32 v66, v181, v179
	v_mul_f32_e32 v82, 0x3fb8aa3b, v66
	ds_read_b128 v[78:81], v177
	ds_read_b128 v[74:77], v177 offset:64
	ds_read_b128 v[70:73], v177 offset:128
	ds_read_b128 v[66:69], v177 offset:192
	v_exp_f32_e32 v82, v82
	ds_read_b128 v[84:87], v178 offset:34816
	v_pk_mul_f32 v[48:49], v[48:49], v[82:83] op_sel_hi:[1,0]
	v_pk_mul_f32 v[46:47], v[46:47], v[82:83] op_sel_hi:[1,0]
	v_pk_mul_f32 v[64:65], v[64:65], v[82:83] op_sel_hi:[1,0]
	v_pk_mul_f32 v[62:63], v[62:63], v[82:83] op_sel_hi:[1,0]
	s_waitcnt lgkmcnt(0)
	v_mfma_f32_16x16x32_bf16 v[46:49], v[78:81], v[84:87], v[46:49]
	ds_read_b128 v[84:87], v178 offset:34880
	v_pk_mul_f32 v[60:61], v[60:61], v[82:83] op_sel_hi:[1,0]
	v_pk_mul_f32 v[58:59], v[58:59], v[82:83] op_sel_hi:[1,0]
	s_waitcnt lgkmcnt(0)
	v_mfma_f32_16x16x32_bf16 v[46:49], v[74:77], v[84:87], v[46:49]
	ds_read_b128 v[84:87], v178 offset:34944
	v_pk_mul_f32 v[52:53], v[52:53], v[82:83] op_sel_hi:[1,0]
	v_pk_mul_f32 v[50:51], v[50:51], v[82:83] op_sel_hi:[1,0]
	s_waitcnt lgkmcnt(0)
	v_mfma_f32_16x16x32_bf16 v[46:49], v[70:73], v[84:87], v[46:49]
	ds_read_b128 v[84:87], v178 offset:35008
	v_pk_mul_f32 v[44:45], v[44:45], v[82:83] op_sel_hi:[1,0]
	v_pk_mul_f32 v[42:43], v[42:43], v[82:83] op_sel_hi:[1,0]
	s_waitcnt lgkmcnt(0)
	v_mfma_f32_16x16x32_bf16 v[46:49], v[66:69], v[84:87], v[46:49]
	ds_read_b128 v[84:87], v178 offset:39168
	v_pk_mul_f32 v[40:41], v[40:41], v[82:83] op_sel_hi:[1,0]
	v_pk_mul_f32 v[38:39], v[38:39], v[82:83] op_sel_hi:[1,0]
	s_waitcnt lgkmcnt(0)
	v_mfma_f32_16x16x32_bf16 v[62:65], v[78:81], v[84:87], v[62:65]
	ds_read_b128 v[84:87], v178 offset:39232
	v_pk_mul_f32 v[36:37], v[36:37], v[82:83] op_sel_hi:[1,0]
	v_pk_mul_f32 v[34:35], v[34:35], v[82:83] op_sel_hi:[1,0]
	s_waitcnt lgkmcnt(0)
	v_mfma_f32_16x16x32_bf16 v[62:65], v[74:77], v[84:87], v[62:65]
	ds_read_b128 v[84:87], v178 offset:39296
	v_pk_mul_f32 v[56:57], v[56:57], v[82:83] op_sel_hi:[1,0]
	v_pk_mul_f32 v[54:55], v[54:55], v[82:83] op_sel_hi:[1,0]
	s_waitcnt lgkmcnt(0)
	v_mfma_f32_16x16x32_bf16 v[62:65], v[70:73], v[84:87], v[62:65]
	ds_read_b128 v[84:87], v178 offset:39360
	s_waitcnt lgkmcnt(0)
	v_mfma_f32_16x16x32_bf16 v[62:65], v[66:69], v[84:87], v[62:65]
	ds_read_b128 v[84:87], v178 offset:43520
	s_waitcnt lgkmcnt(0)
	v_mfma_f32_16x16x32_bf16 v[58:61], v[78:81], v[84:87], v[58:61]
	ds_read_b128 v[84:87], v178 offset:43584
	s_waitcnt lgkmcnt(0)
	v_mfma_f32_16x16x32_bf16 v[58:61], v[74:77], v[84:87], v[58:61]
	ds_read_b128 v[84:87], v178 offset:43648
	s_waitcnt lgkmcnt(0)
	v_mfma_f32_16x16x32_bf16 v[58:61], v[70:73], v[84:87], v[58:61]
	ds_read_b128 v[84:87], v178 offset:43712
	s_waitcnt lgkmcnt(0)
	v_mfma_f32_16x16x32_bf16 v[58:61], v[66:69], v[84:87], v[58:61]
	ds_read_b128 v[84:87], v178 offset:47872
	s_waitcnt lgkmcnt(0)
	v_mfma_f32_16x16x32_bf16 v[50:53], v[78:81], v[84:87], v[50:53]
	ds_read_b128 v[84:87], v178 offset:47936
	s_waitcnt lgkmcnt(0)
	v_mfma_f32_16x16x32_bf16 v[50:53], v[74:77], v[84:87], v[50:53]
	ds_read_b128 v[84:87], v178 offset:48000
	s_waitcnt lgkmcnt(0)
	v_mfma_f32_16x16x32_bf16 v[50:53], v[70:73], v[84:87], v[50:53]
	ds_read_b128 v[84:87], v178 offset:48064
	s_waitcnt lgkmcnt(0)
	v_mfma_f32_16x16x32_bf16 v[50:53], v[66:69], v[84:87], v[50:53]
	ds_read_b128 v[84:87], v178 offset:52224
	s_waitcnt lgkmcnt(0)
	v_mfma_f32_16x16x32_bf16 v[42:45], v[78:81], v[84:87], v[42:45]
	ds_read_b128 v[84:87], v178 offset:52288
	s_waitcnt lgkmcnt(0)
	v_mfma_f32_16x16x32_bf16 v[42:45], v[74:77], v[84:87], v[42:45]
	ds_read_b128 v[84:87], v178 offset:52352
	s_waitcnt lgkmcnt(0)
	v_mfma_f32_16x16x32_bf16 v[42:45], v[70:73], v[84:87], v[42:45]
	ds_read_b128 v[84:87], v178 offset:52416
	s_waitcnt lgkmcnt(0)
	v_mfma_f32_16x16x32_bf16 v[42:45], v[66:69], v[84:87], v[42:45]
	ds_read_b128 v[84:87], v178 offset:56576
	s_waitcnt lgkmcnt(0)
	v_mfma_f32_16x16x32_bf16 v[38:41], v[78:81], v[84:87], v[38:41]
	ds_read_b128 v[84:87], v178 offset:56640
	s_waitcnt lgkmcnt(0)
	v_mfma_f32_16x16x32_bf16 v[38:41], v[74:77], v[84:87], v[38:41]
	ds_read_b128 v[84:87], v178 offset:56704
	s_waitcnt lgkmcnt(0)
	v_mfma_f32_16x16x32_bf16 v[38:41], v[70:73], v[84:87], v[38:41]
	ds_read_b128 v[84:87], v178 offset:56768
	s_waitcnt lgkmcnt(0)
	v_mfma_f32_16x16x32_bf16 v[38:41], v[66:69], v[84:87], v[38:41]
	ds_read_b128 v[84:87], v178 offset:60928
	s_waitcnt lgkmcnt(0)
	v_mfma_f32_16x16x32_bf16 v[34:37], v[78:81], v[84:87], v[34:37]
	ds_read_b128 v[84:87], v178 offset:60992
	s_waitcnt lgkmcnt(0)
	v_mfma_f32_16x16x32_bf16 v[34:37], v[74:77], v[84:87], v[34:37]
	ds_read_b128 v[84:87], v178 offset:61056
	s_waitcnt lgkmcnt(0)
	v_mfma_f32_16x16x32_bf16 v[34:37], v[70:73], v[84:87], v[34:37]
	ds_read_b128 v[84:87], v178 offset:61120
	s_waitcnt lgkmcnt(0)
	v_mfma_f32_16x16x32_bf16 v[34:37], v[66:69], v[84:87], v[34:37]
	ds_read_b128 v[84:87], v178 offset:65280
	s_waitcnt lgkmcnt(0)
	v_mfma_f32_16x16x32_bf16 v[54:57], v[78:81], v[84:87], v[54:57]
	ds_read_b128 v[78:81], v178 offset:65344
	s_waitcnt lgkmcnt(0)
	v_mfma_f32_16x16x32_bf16 v[54:57], v[74:77], v[78:81], v[54:57]
	ds_read_b128 v[74:77], v178 offset:65408
	s_waitcnt lgkmcnt(0)
	v_mfma_f32_16x16x32_bf16 v[54:57], v[70:73], v[74:77], v[54:57]
	ds_read_b128 v[70:73], v178 offset:65472
	s_waitcnt lgkmcnt(0)
	v_mfma_f32_16x16x32_bf16 v[54:57], v[66:69], v[70:73], v[54:57]
	v_mov_b32_e32 v66, 0
	s_and_saveexec_b64 s[96:97], s[4:5]
	s_cbranch_execz .LBB0_667
	v_mov_b32_e32 v66, 0

.LBB0_685:
	s_or_b64 exec, exec, s[90:91]
	s_add_i32 s2, s1, 1
	s_cmp_gt_u32 s1, 14
	s_waitcnt lgkmcnt(0)
	s_barrier
	s_cbranch_scc1 .LBB0_691
	s_lshl_b32 s1, s2, 7
	v_add_u32_e32 v34, s1, v114
	v_add_u32_e32 v36, s1, v116
	v_add_u32_e32 v42, s1, v117
	v_add_u32_e32 v44, s1, v118
	v_sub_u32_e32 v35, 0x7ff, v34
	v_sub_u32_e32 v37, 0x7ff, v36
	v_sub_u32_e32 v43, 0x7ff, v42
	v_sub_u32_e32 v45, 0x7ff, v44
	v_cndmask_b32_e64 v34, v35, v34, s[6:7]
	v_cndmask_b32_e64 v36, v37, v36, s[6:7]
	v_cndmask_b32_e64 v42, v43, v42, s[6:7]
	v_cndmask_b32_e64 v44, v45, v44, s[6:7]
	v_add_u32_e32 v34, s0, v34
	v_add_u32_e32 v36, s0, v36
	v_add_u32_e32 v42, s0, v42
	v_add_u32_e32 v44, s0, v44
	v_ashrrev_i32_e32 v35, 31, v34
	v_ashrrev_i32_e32 v37, 31, v36
	v_ashrrev_i32_e32 v43, 31, v42
	v_ashrrev_i32_e32 v45, 31, v44
	v_lshlrev_b64 v[34:35], 11, v[34:35]
	v_lshlrev_b64 v[36:37], 11, v[36:37]
	v_lshlrev_b64 v[42:43], 11, v[42:43]
	v_lshlrev_b64 v[44:45], 11, v[44:45]
	v_lshl_add_u64 v[34:35], v[108:109], 0, v[34:35]
	v_lshl_add_u64 v[38:39], v[108:109], 0, v[36:37]
	v_lshl_add_u64 v[42:43], v[108:109], 0, v[42:43]
	v_lshl_add_u64 v[46:47], v[108:109], 0, v[44:45]
	global_load_dwordx4 v[34:37], v[34:35], off offset:1024
	s_nop 0
	global_load_dwordx4 v[38:41], v[38:39], off offset:1024
	s_nop 0
	global_load_dwordx4 v[42:45], v[42:43], off offset:1024
	s_nop 0
	global_load_dwordx4 v[46:49], v[46:47], off offset:1024
	s_and_saveexec_b64 s[90:91], s[8:9]
	s_cbranch_execz .LBB0_688
	v_or_b32_e32 v60, s1, v120
	v_sub_u32_e32 v50, 0x7ff, v60
	v_cndmask_b32_e64 v50, v50, v60, s[6:7]
	v_or_b32_e32 v52, 1, v60
	v_xad_u32 v53, v60, -2, v216
	v_or_b32_e32 v58, 2, v60
	v_xad_u32 v59, v60, -3, v216
	v_or_b32_e32 v61, 3, v60
	v_xad_u32 v60, v60, -4, v216
	v_cndmask_b32_e64 v52, v53, v52, s[6:7]
	v_cndmask_b32_e64 v58, v59, v58, s[6:7]
	v_cndmask_b32_e64 v60, v60, v61, s[6:7]
	v_add_u32_e32 v50, s0, v50
	v_add_u32_e32 v52, s0, v52
	v_add_u32_e32 v58, s0, v58
	v_add_u32_e32 v60, s0, v60
	v_ashrrev_i32_e32 v51, 31, v50
	v_ashrrev_i32_e32 v53, 31, v52
	v_ashrrev_i32_e32 v59, 31, v58
	v_ashrrev_i32_e32 v61, 31, v60
	v_lshlrev_b64 v[50:51], 11, v[50:51]
	v_lshlrev_b64 v[52:53], 11, v[52:53]
	v_lshlrev_b64 v[58:59], 11, v[58:59]
	v_lshlrev_b64 v[60:61], 11, v[60:61]
	v_lshl_add_u64 v[50:51], v[106:107], 0, v[50:51]
	v_lshl_add_u64 v[54:55], v[106:107], 0, v[52:53]
	v_lshl_add_u64 v[58:59], v[106:107], 0, v[58:59]
	v_lshl_add_u64 v[62:63], v[106:107], 0, v[60:61]
	global_load_dwordx4 v[50:53], v[50:51], off
	s_nop 0
	global_load_dwordx4 v[54:57], v[54:55], off
	s_nop 0
	global_load_dwordx4 v[58:61], v[58:59], off
	s_nop 0
	global_load_dwordx4 v[62:65], v[62:63], off

.LBB0_691:
	ds_read_b32 v155, v125
	s_waitcnt vmcnt(3)
	v_and_b32_e32 v187, 0xffff0000, v78
	v_lshlrev_b32_e32 v186, 16, v78
	s_waitcnt vmcnt(2)
	v_and_b32_e32 v191, 0xffff0000, v74
	v_and_b32_e32 v190, 0xffff0000, v80
	s_waitcnt lgkmcnt(0)
	v_sub_f32_e32 v82, v154, v155
	v_mul_f32_e32 v156, 0x3fb8aa3b, v82
	ds_read_b128 v[82:85], v138
	ds_read_b128 v[86:89], v138 offset:1088
	ds_read_b128 v[90:93], v138 offset:64
	ds_read_b128 v[94:97], v138 offset:1152
	v_lshlrev_b64 v[110:111], 10, v[110:111]
	s_waitcnt lgkmcnt(3)
	v_mfma_f32_16x16x32_bf16 v[82:85], v[82:85], v[78:81], 0
	s_mov_b32 s90, 0
	s_waitcnt lgkmcnt(2)
	v_mfma_f32_16x16x32_bf16 v[86:89], v[86:89], v[78:81], 0
	s_waitcnt lgkmcnt(1)
	v_mfma_f32_16x16x32_bf16 v[82:85], v[90:93], v[74:77], v[82:85]
	s_waitcnt lgkmcnt(0)
	v_mfma_f32_16x16x32_bf16 v[86:89], v[94:97], v[74:77], v[86:89]
	ds_read_b128 v[90:93], v138 offset:128
	ds_read_b128 v[94:97], v138 offset:1216
	s_waitcnt vmcnt(1) lgkmcnt(1)
	v_mfma_f32_16x16x32_bf16 v[82:85], v[90:93], v[70:73], v[82:85]
	s_waitcnt lgkmcnt(0)
	v_mfma_f32_16x16x32_bf16 v[86:89], v[94:97], v[70:73], v[86:89]
	ds_read_b128 v[90:93], v138 offset:192
	ds_read_b128 v[94:97], v138 offset:1280
	s_waitcnt vmcnt(0) lgkmcnt(1)
	v_mfma_f32_16x16x32_bf16 v[82:85], v[90:93], v[66:69], v[82:85]
	s_waitcnt lgkmcnt(0)
	v_mfma_f32_16x16x32_bf16 v[86:89], v[94:97], v[66:69], v[86:89]
	ds_read_b128 v[90:93], v127
	ds_read_b128 v[94:97], v127 offset:16
	s_waitcnt lgkmcnt(1)
	v_sub_f32_e32 v90, v90, v155
	v_sub_f32_e32 v91, v91, v155
	v_mul_f32_e32 v90, 0x3fb8aa3b, v90
	v_mul_f32_e32 v91, 0x3fb8aa3b, v91
	v_exp_f32_e32 v90, v90
	v_exp_f32_e32 v91, v91
	v_mul_f32_e32 v82, v82, v90
	v_mul_f32_e32 v83, v83, v91
	v_cndmask_b32_e64 v90, v82, 0, s[24:25]
	s_waitcnt lgkmcnt(0)
	v_sub_f32_e32 v82, v94, v155
	v_cndmask_b32_e64 v91, 0, v83, s[26:27]
	v_sub_f32_e32 v83, v95, v155
	v_mul_f32_e32 v82, 0x3fb8aa3b, v82
	v_mul_f32_e32 v83, 0x3fb8aa3b, v83
	v_exp_f32_e32 v82, v82
	v_exp_f32_e32 v83, v83
	s_nop 0
	v_pk_mul_f32 v[82:83], v[86:87], v[82:83]
	s_nop 0
	v_cndmask_b32_e64 v95, v83, 0, s[28:29]
	v_sub_f32_e32 v83, v96, v155
	v_mul_f32_e32 v83, 0x3fb8aa3b, v83
	v_cndmask_b32_e64 v98, v82, 0, s[30:31]
	v_sub_f32_e32 v82, v92, v155
	v_exp_f32_e32 v86, v83
	v_sub_f32_e32 v83, v93, v155
	v_mul_f32_e32 v82, 0x3fb8aa3b, v82
	v_mul_f32_e32 v83, 0x3fb8aa3b, v83
	v_exp_f32_e32 v82, v82
	v_exp_f32_e32 v83, v83
	s_nop 0
	v_pk_mul_f32 v[82:83], v[84:85], v[82:83]
	s_nop 0
	v_cndmask_b32_e64 v85, v82, 0, s[36:37]
	v_sub_f32_e32 v82, v97, v155
	v_mul_f32_e32 v82, 0x3fb8aa3b, v82
	v_exp_f32_e32 v87, v82
	v_cndmask_b32_e64 v84, v83, 0, s[34:35]
	v_pk_mul_f32 v[82:83], v[88:89], v[86:87]
	s_nop 0
	v_cndmask_b32_e64 v87, v82, 0, s[40:41]
	v_add_f32_e32 v82, 0, v90
	v_add_f32_e32 v82, v91, v82
	v_add_f32_e32 v82, v85, v82
	v_add_f32_e32 v82, v84, v82
	v_add_f32_e32 v82, v98, v82
	v_add_f32_e32 v82, v95, v82
	v_cndmask_b32_e64 v86, v83, 0, s[38:39]
	v_add_f32_e32 v82, v87, v82
	v_add_f32_e32 v94, v86, v82
	v_cvt_pk_bf16_f32 v82, v90, v91
	v_cvt_pk_bf16_f32 v83, v85, v84
	v_cvt_pk_bf16_f32 v85, v87, v86
	ds_read_b128 v[86:89], v138 offset:8704
	ds_read_b128 v[90:93], v138 offset:9792
	v_cvt_pk_bf16_f32 v84, v98, v95
	ds_read_b128 v[96:99], v138 offset:8768
	ds_read_b128 v[158:161], v138 offset:9856
	s_waitcnt lgkmcnt(3)
	v_mfma_f32_16x16x32_bf16 v[86:89], v[86:89], v[78:81], 0
	s_waitcnt lgkmcnt(2)
	v_mfma_f32_16x16x32_bf16 v[90:93], v[90:93], v[78:81], 0
	s_waitcnt lgkmcnt(1)
	v_mfma_f32_16x16x32_bf16 v[86:89], v[96:99], v[74:77], v[86:89]
	s_waitcnt lgkmcnt(0)
	v_mfma_f32_16x16x32_bf16 v[90:93], v[158:161], v[74:77], v[90:93]
	ds_read_b128 v[96:99], v138 offset:8832
	ds_read_b128 v[158:161], v138 offset:9920
	s_waitcnt lgkmcnt(1)
	v_mfma_f32_16x16x32_bf16 v[86:89], v[96:99], v[70:73], v[86:89]
	s_waitcnt lgkmcnt(0)
	v_mfma_f32_16x16x32_bf16 v[96:99], v[158:161], v[70:73], v[90:93]
	s_nop 2
	ds_read_b128 v[90:93], v138 offset:8896
	ds_read_b128 v[158:161], v138 offset:9984
	s_waitcnt lgkmcnt(1)
	v_mfma_f32_16x16x32_bf16 v[90:93], v[90:93], v[66:69], v[86:89]
	s_waitcnt lgkmcnt(0)
	v_mfma_f32_16x16x32_bf16 v[86:89], v[158:161], v[66:69], v[96:99]
	s_nop 2
	ds_read_b128 v[96:99], v127 offset:128
	ds_read_b128 v[158:161], v127 offset:144
	s_waitcnt lgkmcnt(1)
	v_sub_f32_e32 v95, v96, v155
	v_mul_f32_e32 v95, 0x3fb8aa3b, v95
	v_exp_f32_e32 v96, v95
	s_waitcnt lgkmcnt(0)
	v_sub_f32_e32 v95, v158, v155
	v_mul_f32_e32 v95, 0x3fb8aa3b, v95
	v_exp_f32_e32 v100, v95
	v_sub_f32_e32 v95, v97, v155
	v_mul_f32_e32 v95, 0x3fb8aa3b, v95
	v_exp_f32_e32 v97, v95
	s_nop 0
	v_pk_mul_f32 v[90:91], v[90:91], v[96:97]
	s_nop 0
	v_cndmask_b32_e64 v96, v90, 0, s[44:45]
	v_sub_f32_e32 v90, v159, v155
	v_mul_f32_e32 v90, 0x3fb8aa3b, v90
	v_exp_f32_e32 v101, v90
	v_cndmask_b32_e64 v95, v91, 0, s[42:43]
	v_pk_mul_f32 v[86:87], v[86:87], v[100:101]
	s_nop 0
	v_cndmask_b32_e64 v97, v87, 0, s[46:47]
	v_sub_f32_e32 v87, v160, v155
	v_mul_f32_e32 v87, 0x3fb8aa3b, v87
	v_cndmask_b32_e64 v100, v86, 0, s[48:49]
	v_sub_f32_e32 v86, v98, v155
	v_exp_f32_e32 v90, v87
	v_sub_f32_e32 v87, v99, v155
	v_mul_f32_e32 v86, 0x3fb8aa3b, v86
	v_mul_f32_e32 v87, 0x3fb8aa3b, v87
	v_exp_f32_e32 v86, v86
	v_exp_f32_e32 v87, v87
	s_nop 0
	v_pk_mul_f32 v[86:87], v[92:93], v[86:87]
	s_nop 0
	v_cndmask_b32_e64 v93, v86, 0, s[52:53]
	v_sub_f32_e32 v86, v161, v155
	v_mul_f32_e32 v86, 0x3fb8aa3b, v86
	v_exp_f32_e32 v91, v86
	v_cndmask_b32_e64 v92, v87, 0, s[50:51]
	v_pk_mul_f32 v[86:87], v[88:89], v[90:91]
	s_nop 0
	v_cndmask_b32_e64 v90, v86, 0, s[56:57]
	v_add_f32_e32 v86, v94, v96
	v_add_f32_e32 v86, v95, v86
	v_add_f32_e32 v86, v93, v86
	v_add_f32_e32 v86, v92, v86
	v_add_f32_e32 v86, v100, v86
	v_add_f32_e32 v86, v97, v86
	v_cndmask_b32_e64 v89, v87, 0, s[54:55]
	v_add_f32_e32 v86, v90, v86
	v_add_f32_e32 v98, v89, v86
	v_cvt_pk_bf16_f32 v86, v96, v95
	v_cvt_pk_bf16_f32 v87, v93, v92
	v_cvt_pk_bf16_f32 v88, v100, v97
	v_cvt_pk_bf16_f32 v89, v90, v89
	ds_read_b128 v[90:93], v138 offset:17408
	ds_read_b128 v[94:97], v138 offset:18496
	ds_read_b128 v[158:161], v138 offset:17472
	ds_read_b128 v[176:179], v138 offset:18560
	s_waitcnt lgkmcnt(3)
	v_mfma_f32_16x16x32_bf16 v[90:93], v[90:93], v[78:81], 0
	s_waitcnt lgkmcnt(2)
	v_mfma_f32_16x16x32_bf16 v[94:97], v[94:97], v[78:81], 0
	s_waitcnt lgkmcnt(1)
	v_mfma_f32_16x16x32_bf16 v[90:93], v[158:161], v[74:77], v[90:93]
	s_waitcnt lgkmcnt(0)
	v_mfma_f32_16x16x32_bf16 v[94:97], v[176:179], v[74:77], v[94:97]
	ds_read_b128 v[158:161], v138 offset:17536
	ds_read_b128 v[176:179], v138 offset:18624
	s_waitcnt lgkmcnt(1)
	v_mfma_f32_16x16x32_bf16 v[90:93], v[158:161], v[70:73], v[90:93]
	s_waitcnt lgkmcnt(0)
	v_mfma_f32_16x16x32_bf16 v[158:161], v[176:179], v[70:73], v[94:97]
	s_nop 2
	ds_read_b128 v[94:97], v138 offset:17600
	ds_read_b128 v[176:179], v138 offset:18688
	s_waitcnt lgkmcnt(1)
	v_mfma_f32_16x16x32_bf16 v[94:97], v[94:97], v[66:69], v[90:93]
	s_waitcnt lgkmcnt(0)
	v_mfma_f32_16x16x32_bf16 v[90:93], v[176:179], v[66:69], v[158:161]
	s_nop 2
	ds_read_b128 v[158:161], v127 offset:256
	ds_read_b128 v[176:179], v127 offset:272
	s_waitcnt lgkmcnt(1)
	v_sub_f32_e32 v99, v158, v155
	v_mul_f32_e32 v99, 0x3fb8aa3b, v99
	v_exp_f32_e32 v100, v99
	s_waitcnt lgkmcnt(0)
	v_sub_f32_e32 v99, v176, v155
	v_mul_f32_e32 v99, 0x3fb8aa3b, v99
	v_exp_f32_e32 v158, v99
	v_sub_f32_e32 v99, v159, v155
	v_mul_f32_e32 v99, 0x3fb8aa3b, v99
	v_exp_f32_e32 v101, v99
	s_nop 0
	v_pk_mul_f32 v[94:95], v[94:95], v[100:101]
	s_nop 0
	v_cndmask_b32_e64 v100, v94, 0, s[60:61]
	v_sub_f32_e32 v94, v177, v155
	v_mul_f32_e32 v94, 0x3fb8aa3b, v94
	v_exp_f32_e32 v159, v94
	v_cndmask_b32_e64 v99, v95, 0, s[58:59]
	v_pk_mul_f32 v[90:91], v[90:91], v[158:159]
	s_nop 0
	v_cndmask_b32_e64 v101, v91, 0, s[62:63]
	v_sub_f32_e32 v91, v178, v155
	v_mul_f32_e32 v91, 0x3fb8aa3b, v91
	v_cndmask_b32_e64 v158, v90, 0, s[64:65]
	v_sub_f32_e32 v90, v160, v155
	v_exp_f32_e32 v94, v91
	v_sub_f32_e32 v91, v161, v155
	v_mul_f32_e32 v90, 0x3fb8aa3b, v90
	v_mul_f32_e32 v91, 0x3fb8aa3b, v91
	v_exp_f32_e32 v90, v90
	v_exp_f32_e32 v91, v91
	s_nop 0
	v_pk_mul_f32 v[90:91], v[96:97], v[90:91]
	s_nop 0
	v_cndmask_b32_e64 v97, v90, 0, s[68:69]
	v_sub_f32_e32 v90, v179, v155
	v_mul_f32_e32 v90, 0x3fb8aa3b, v90
	v_exp_f32_e32 v95, v90
	v_cndmask_b32_e64 v96, v91, 0, s[66:67]
	v_pk_mul_f32 v[90:91], v[92:93], v[94:95]
	s_nop 0
	v_cndmask_b32_e64 v94, v90, 0, s[72:73]
	v_add_f32_e32 v90, v98, v100
	v_add_f32_e32 v90, v99, v90
	v_add_f32_e32 v90, v97, v90
	v_add_f32_e32 v90, v96, v90
	v_add_f32_e32 v90, v158, v90
	v_add_f32_e32 v90, v101, v90
	v_cndmask_b32_e64 v93, v91, 0, s[70:71]
	v_add_f32_e32 v90, v94, v90
	v_add_f32_e32 v157, v93, v90
	v_cvt_pk_bf16_f32 v90, v100, v99
	v_cvt_pk_bf16_f32 v91, v97, v96
	v_cvt_pk_bf16_f32 v92, v158, v101
	v_cvt_pk_bf16_f32 v93, v94, v93
	ds_read_b128 v[94:97], v138 offset:26112
	ds_read_b128 v[98:101], v138 offset:27200
	ds_read_b128 v[158:161], v138 offset:26176
	ds_read_b128 v[176:179], v138 offset:27264
	s_waitcnt lgkmcnt(3)
	v_mfma_f32_16x16x32_bf16 v[94:97], v[94:97], v[78:81], 0
	s_waitcnt lgkmcnt(2)
	v_mfma_f32_16x16x32_bf16 v[98:101], v[98:101], v[78:81], 0
	s_waitcnt lgkmcnt(1)
	v_mfma_f32_16x16x32_bf16 v[94:97], v[158:161], v[74:77], v[94:97]
	s_waitcnt lgkmcnt(0)
	v_mfma_f32_16x16x32_bf16 v[98:101], v[176:179], v[74:77], v[98:101]
	ds_read_b128 v[158:161], v138 offset:26240
	ds_read_b128 v[176:179], v138 offset:27328
	s_waitcnt lgkmcnt(1)
	v_mfma_f32_16x16x32_bf16 v[94:97], v[158:161], v[70:73], v[94:97]
	s_waitcnt lgkmcnt(0)
	v_mfma_f32_16x16x32_bf16 v[158:161], v[176:179], v[70:73], v[98:101]
	s_nop 2
	ds_read_b128 v[98:101], v138 offset:26304
	ds_read_b128 v[176:179], v138 offset:27392
	s_waitcnt lgkmcnt(1)
	v_mfma_f32_16x16x32_bf16 v[98:101], v[98:101], v[66:69], v[94:97]
	s_waitcnt lgkmcnt(0)
	v_mfma_f32_16x16x32_bf16 v[94:97], v[176:179], v[66:69], v[158:161]
	s_nop 2
	ds_read_b128 v[158:161], v127 offset:384
	ds_read_b128 v[176:179], v127 offset:400
	s_waitcnt lgkmcnt(1)
	v_sub_f32_e32 v158, v158, v155
	v_sub_f32_e32 v159, v159, v155
	v_mul_f32_e32 v158, 0x3fb8aa3b, v158
	v_mul_f32_e32 v159, 0x3fb8aa3b, v159
	v_exp_f32_e32 v158, v158
	v_exp_f32_e32 v159, v159
	s_waitcnt lgkmcnt(0)
	v_sub_f32_e32 v169, v176, v155
	v_mul_f32_e32 v169, 0x3fb8aa3b, v169
	v_exp_f32_e32 v176, v169
	v_pk_mul_f32 v[98:99], v[98:99], v[158:159]
	s_nop 0
	v_cndmask_b32_e64 v159, v98, 0, s[76:77]
	v_sub_f32_e32 v98, v177, v155
	v_mul_f32_e32 v98, 0x3fb8aa3b, v98
	v_exp_f32_e32 v177, v98
	v_cndmask_b32_e64 v158, v99, 0, s[74:75]
	v_pk_mul_f32 v[94:95], v[94:95], v[176:177]
	s_nop 0
	v_cndmask_b32_e64 v176, v95, 0, s[78:79]
	v_sub_f32_e32 v95, v178, v155
	v_mul_f32_e32 v95, 0x3fb8aa3b, v95
	v_cndmask_b32_e64 v180, v94, 0, s[80:81]
	v_sub_f32_e32 v94, v160, v155
	v_exp_f32_e32 v98, v95
	v_sub_f32_e32 v95, v161, v155
	v_mul_f32_e32 v94, 0x3fb8aa3b, v94
	v_mul_f32_e32 v95, 0x3fb8aa3b, v95
	v_exp_f32_e32 v94, v94
	v_exp_f32_e32 v95, v95
	s_nop 0
	v_pk_mul_f32 v[94:95], v[100:101], v[94:95]
	s_nop 0
	v_cndmask_b32_e64 v101, v94, 0, s[84:85]
	v_sub_f32_e32 v94, v179, v155
	v_mul_f32_e32 v94, 0x3fb8aa3b, v94
	v_exp_f32_e32 v99, v94
	v_cndmask_b32_e64 v100, v95, 0, s[82:83]
	v_pk_mul_f32 v[94:95], v[96:97], v[98:99]
	s_nop 0
	v_cndmask_b32_e64 v182, v94, 0, s[88:89]
	v_add_f32_e32 v94, v157, v159
	v_add_f32_e32 v94, v158, v94
	v_add_u32_e32 v98, 0, v126
	v_add_f32_e32 v94, v101, v94
	v_add_u32_e32 v157, 0x22600, v98
	v_cndmask_b32_e64 v178, v95, 0, s[86:87]
	v_add_f32_e32 v184, v100, v94
	v_cvt_pk_bf16_f32 v94, v159, v158
	v_cvt_pk_bf16_f32 v95, v101, v100
	ds_read_b128 v[98:101], v157
	ds_read_b128 v[158:161], v157 offset:16
	v_cvt_pk_bf16_f32 v96, v180, v176
	v_cvt_pk_bf16_f32 v97, v182, v178
	s_waitcnt lgkmcnt(1)
	v_pk_mul_f32 v[98:99], v[98:99], v[186:187]
	v_and_b32_e32 v187, 0xffff0000, v79
	v_lshlrev_b32_e32 v186, 16, v79
	v_pk_mul_f32 v[100:101], v[100:101], v[186:187]
	v_add_f32_e32 v98, v98, v99
	v_add_f32_e32 v98, v100, v98
	v_add_f32_e32 v98, v101, v98
	v_add_f32_e32 v169, 0, v98
	ds_read_b128 v[98:101], v157 offset:128
	v_lshlrev_b32_e32 v187, 16, v74
	v_lshlrev_b32_e32 v186, 16, v80
	s_waitcnt lgkmcnt(1)
	v_mov_b32_e32 v188, v158
	v_lshlrev_b32_e32 v158, 16, v81
	s_waitcnt lgkmcnt(0)
	v_mov_b32_e32 v189, v98
	v_mov_b32_e32 v98, v159
	v_pk_mul_f32 v[98:99], v[98:99], v[190:191]
	v_lshlrev_b32_e32 v159, 16, v75
	v_pk_fma_f32 v[98:99], v[188:189], v[186:187], v[98:99]
	v_mov_b32_e32 v186, v160
	v_mov_b32_e32 v187, v100
	v_pk_fma_f32 v[98:99], v[186:187], v[158:159], v[98:99]
	v_and_b32_e32 v159, 0xffff0000, v75
	v_and_b32_e32 v158, 0xffff0000, v81
	v_mov_b32_e32 v100, v161
	v_pk_fma_f32 v[98:99], v[100:101], v[158:159], v[98:99]
	v_and_b32_e32 v191, 0xffff0000, v70
	v_add_f32_e32 v98, v169, v98
	v_add_f32_e32 v169, v98, v99
	ds_read_b128 v[98:101], v157 offset:144
	ds_read_b128 v[158:161], v157 offset:256
	v_and_b32_e32 v190, 0xffff0000, v76
	v_lshlrev_b32_e32 v187, 16, v70
	v_lshlrev_b32_e32 v186, 16, v76
	s_waitcnt lgkmcnt(1)
	v_mov_b32_e32 v188, v98
	s_waitcnt lgkmcnt(0)
	v_mov_b32_e32 v189, v158
	v_mov_b32_e32 v158, v99
	v_pk_mul_f32 v[98:99], v[158:159], v[190:191]
	v_lshlrev_b32_e32 v159, 16, v71
	v_pk_fma_f32 v[98:99], v[188:189], v[186:187], v[98:99]
	v_lshlrev_b32_e32 v158, 16, v77
	v_mov_b32_e32 v186, v100
	v_mov_b32_e32 v187, v160
	v_pk_fma_f32 v[98:99], v[186:187], v[158:159], v[98:99]
	v_and_b32_e32 v159, 0xffff0000, v71
	v_and_b32_e32 v158, 0xffff0000, v77
	v_mov_b32_e32 v160, v101
	v_pk_fma_f32 v[98:99], v[160:161], v[158:159], v[98:99]
	v_and_b32_e32 v191, 0xffff0000, v66
	v_add_f32_e32 v98, v169, v98
	v_add_f32_e32 v169, v98, v99
	ds_read_b128 v[98:101], v157 offset:272
	ds_read_b128 v[158:161], v157 offset:384
	v_and_b32_e32 v190, 0xffff0000, v72
	v_lshlrev_b32_e32 v187, 16, v66
	v_lshlrev_b32_e32 v186, 16, v72
	s_waitcnt lgkmcnt(1)
	v_mov_b32_e32 v188, v98
	s_waitcnt lgkmcnt(0)
	v_mov_b32_e32 v189, v158
	v_mov_b32_e32 v158, v99
	v_pk_mul_f32 v[98:99], v[158:159], v[190:191]
	v_lshlrev_b32_e32 v159, 16, v67
	v_pk_fma_f32 v[98:99], v[188:189], v[186:187], v[98:99]
	v_lshlrev_b32_e32 v158, 16, v73
	v_mov_b32_e32 v186, v100
	v_mov_b32_e32 v187, v160
	v_pk_fma_f32 v[98:99], v[186:187], v[158:159], v[98:99]
	v_and_b32_e32 v159, 0xffff0000, v67
	v_and_b32_e32 v158, 0xffff0000, v73
	v_mov_b32_e32 v160, v101
	v_pk_fma_f32 v[98:99], v[160:161], v[158:159], v[98:99]
	s_nop 0
	v_add_f32_e32 v98, v169, v98
	v_add_f32_e32 v179, v98, v99
	ds_read_b128 v[98:101], v157 offset:400
	v_lshlrev_b32_e32 v157, 16, v68
	s_waitcnt lgkmcnt(0)
	v_mul_f32_e32 v181, v98, v157
	v_and_b32_e32 v98, 0xffff0000, v68
	v_mul_f32_e32 v185, v99, v98
	v_lshlrev_b32_e32 v98, 16, v69
	v_mul_f32_e32 v177, v100, v98
	v_and_b32_e32 v98, 0xffff0000, v69
	v_mul_f32_e32 v183, v101, v98
	v_pk_add_f32 v[100:101], v[180:181], v[184:185]
	v_exp_f32_e32 v98, v156
	v_pk_add_f32 v[100:101], v[176:177], v[100:101]
	ds_read_b32 v99, v130
	v_pk_add_f32 v[100:101], v[182:183], v[100:101]
	s_nop 0
	v_pk_add_f32 v[100:101], v[178:179], v[100:101]
	ds_bpermute_b32 v156, v128, v100
	ds_bpermute_b32 v157, v128, v101
	ds_read_b128 v[176:179], v148 offset:64
	s_waitcnt lgkmcnt(3)
	v_add_f32_e32 v99, v155, v99
	v_mul_f32_e32 v99, 0xbfb8aa3b, v99
	v_exp_f32_e32 v99, v99
	s_waitcnt lgkmcnt(1)
	v_pk_add_f32 v[100:101], v[100:101], v[156:157]
	ds_bpermute_b32 v156, v129, v100
	ds_bpermute_b32 v157, v129, v101
	s_waitcnt lgkmcnt(0)
	v_pk_add_f32 v[100:101], v[100:101], v[156:157]
	s_nop 0
	v_fmac_f32_e32 v100, v98, v101
	v_max_f32_e64 v99, |v100|, v99
	v_div_scale_f32 v100, s[96:97], v99, v99, 1.0
	v_rcp_f32_e32 v101, v100
	v_readlane_b32 s96, v254, 25
	v_readlane_b32 s97, v254, 26
	s_load_dwordx2 s[96:97], s[96:97], 0x118
	v_fma_f32 v155, -v100, v101, 1.0
	v_fmac_f32_e32 v101, v155, v101
	v_div_scale_f32 v155, vcc, 1.0, v99, 1.0
	v_mul_f32_e32 v156, v155, v101
	v_fma_f32 v157, -v100, v156, v155
	v_fmac_f32_e32 v156, v157, v101
	v_fma_f32 v100, -v100, v156, v155
	v_div_fmas_f32 v100, v100, v101, v156
	ds_read_b128 v[156:159], v148
	s_waitcnt lgkmcnt(0)
	v_mfma_f32_16x16x32_bf16 v[156:159], v[156:159], v[78:81], 0
	v_lshl_add_u64 v[112:113], s[96:97], 0, v[112:113]
	s_mov_b64 s[96:97], 0x2134200
	v_lshl_add_u64 v[112:113], v[112:113], 0, s[96:97]
	v_mfma_f32_16x16x32_bf16 v[156:159], v[176:179], v[74:77], v[156:159]
	ds_read_b128 v[176:179], v148 offset:128
	v_readlane_b32 s96, v254, 60
	v_readlane_b32 s97, v254, 61
	s_waitcnt lgkmcnt(0)
	v_mfma_f32_16x16x32_bf16 v[156:159], v[176:179], v[70:73], v[156:159]
	ds_read_b128 v[176:179], v148 offset:192
	v_lshl_add_u64 v[110:111], s[96:97], 0, v[110:111]
	v_readlane_b32 s96, v254, 19
	s_waitcnt lgkmcnt(0)
	v_mfma_f32_16x16x32_bf16 v[156:159], v[176:179], v[66:69], v[156:159]
	ds_read_b128 v[176:179], v149
	v_div_fixup_f32 v100, v100, v99, 1.0
	v_cndmask_b32_e64 v111, v111, v113, s[6:7]
	s_nop 4
	v_pk_mul_f32 v[158:159], v[98:99], v[158:159] op_sel_hi:[0,1]
	v_pk_mul_f32 v[156:157], v[98:99], v[156:157] op_sel_hi:[0,1]
	v_cndmask_b32_e64 v110, v110, v112, s[6:7]
	v_readlane_b32 s97, v254, 20
	s_waitcnt lgkmcnt(0)
	v_mfma_f32_16x16x32_bf16 v[156:159], v[176:179], v[82:85], v[156:159]
	ds_read_b128 v[176:179], v149 offset:64
	v_lshl_add_u64 v[110:111], v[110:111], 0, s[96:97]
	v_lshl_add_u64 v[110:111], v[110:111], 0, v[0:1]
	s_waitcnt lgkmcnt(0)
	v_mfma_f32_16x16x32_bf16 v[156:159], v[176:179], v[86:89], v[156:159]
	ds_read_b128 v[176:179], v149 offset:128
	s_waitcnt lgkmcnt(0)
	v_mfma_f32_16x16x32_bf16 v[156:159], v[176:179], v[90:93], v[156:159]
	ds_read_b128 v[176:179], v149 offset:192
	s_waitcnt lgkmcnt(0)
	v_mfma_f32_16x16x32_bf16 v[156:159], v[176:179], v[94:97], v[156:159]
	ds_read_b128 v[176:179], v148 offset:4416
	s_nop 6
	v_pk_mul_f32 v[112:113], v[100:101], v[158:159] op_sel_hi:[0,1]
	v_pk_mul_f32 v[156:157], v[100:101], v[156:157] op_sel_hi:[0,1]
	v_cvt_pk_bf16_f32 v156, v156, v157
	v_cvt_pk_bf16_f32 v157, v112, v113
	global_store_dwordx2 v[110:111], v[156:157], off
	ds_read_b128 v[156:159], v148 offset:4352
	s_waitcnt lgkmcnt(0)
	v_mfma_f32_16x16x32_bf16 v[156:159], v[156:159], v[78:81], 0
	v_mfma_f32_16x16x32_bf16 v[156:159], v[176:179], v[74:77], v[156:159]
	ds_read_b128 v[176:179], v148 offset:4480
	s_waitcnt lgkmcnt(0)
	v_mfma_f32_16x16x32_bf16 v[156:159], v[176:179], v[70:73], v[156:159]
	ds_read_b128 v[176:179], v148 offset:4544
	s_waitcnt lgkmcnt(0)
	v_mfma_f32_16x16x32_bf16 v[156:159], v[176:179], v[66:69], v[156:159]
	ds_read_b128 v[176:179], v149 offset:4352
	s_nop 6
	v_pk_mul_f32 v[158:159], v[98:99], v[158:159] op_sel_hi:[0,1]
	v_pk_mul_f32 v[156:157], v[98:99], v[156:157] op_sel_hi:[0,1]
	s_waitcnt lgkmcnt(0)
	s_nop 0
	v_mfma_f32_16x16x32_bf16 v[156:159], v[176:179], v[82:85], v[156:159]
	ds_read_b128 v[176:179], v149 offset:4416
	s_waitcnt lgkmcnt(0)
	v_mfma_f32_16x16x32_bf16 v[156:159], v[176:179], v[86:89], v[156:159]
	ds_read_b128 v[176:179], v149 offset:4480
	s_waitcnt lgkmcnt(0)
	v_mfma_f32_16x16x32_bf16 v[156:159], v[176:179], v[90:93], v[156:159]
	ds_read_b128 v[176:179], v149 offset:4544
	s_waitcnt lgkmcnt(0)
	v_mfma_f32_16x16x32_bf16 v[156:159], v[176:179], v[94:97], v[156:159]
	ds_read_b128 v[176:179], v148 offset:8768
	s_nop 6
	v_pk_mul_f32 v[112:113], v[100:101], v[158:159] op_sel_hi:[0,1]
	v_pk_mul_f32 v[156:157], v[100:101], v[156:157] op_sel_hi:[0,1]
	v_cvt_pk_bf16_f32 v156, v156, v157
	v_cvt_pk_bf16_f32 v157, v112, v113
	global_store_dwordx2 v[110:111], v[156:157], off offset:32
	ds_read_b128 v[156:159], v148 offset:8704
	s_waitcnt lgkmcnt(0)
	v_mfma_f32_16x16x32_bf16 v[156:159], v[156:159], v[78:81], 0
	v_mfma_f32_16x16x32_bf16 v[156:159], v[176:179], v[74:77], v[156:159]
	ds_read_b128 v[176:179], v148 offset:8832
	s_waitcnt lgkmcnt(0)
	v_mfma_f32_16x16x32_bf16 v[156:159], v[176:179], v[70:73], v[156:159]
	ds_read_b128 v[176:179], v148 offset:8896
	s_waitcnt lgkmcnt(0)
	v_mfma_f32_16x16x32_bf16 v[156:159], v[176:179], v[66:69], v[156:159]
	ds_read_b128 v[176:179], v149 offset:8704
	s_nop 6
	v_pk_mul_f32 v[158:159], v[98:99], v[158:159] op_sel_hi:[0,1]
	v_pk_mul_f32 v[156:157], v[98:99], v[156:157] op_sel_hi:[0,1]
	s_waitcnt lgkmcnt(0)
	s_nop 0
	v_mfma_f32_16x16x32_bf16 v[156:159], v[176:179], v[82:85], v[156:159]
	ds_read_b128 v[176:179], v149 offset:8768
	s_waitcnt lgkmcnt(0)
	v_mfma_f32_16x16x32_bf16 v[156:159], v[176:179], v[86:89], v[156:159]
	ds_read_b128 v[176:179], v149 offset:8832
	s_waitcnt lgkmcnt(0)
	v_mfma_f32_16x16x32_bf16 v[156:159], v[176:179], v[90:93], v[156:159]
	ds_read_b128 v[176:179], v149 offset:8896
	s_waitcnt lgkmcnt(0)
	v_mfma_f32_16x16x32_bf16 v[156:159], v[176:179], v[94:97], v[156:159]
	ds_read_b128 v[176:179], v148 offset:13120
	s_nop 6
	v_pk_mul_f32 v[112:113], v[100:101], v[158:159] op_sel_hi:[0,1]
	v_pk_mul_f32 v[156:157], v[100:101], v[156:157] op_sel_hi:[0,1]
	v_cvt_pk_bf16_f32 v156, v156, v157
	v_cvt_pk_bf16_f32 v157, v112, v113
	global_store_dwordx2 v[110:111], v[156:157], off offset:64
	ds_read_b128 v[156:159], v148 offset:13056
	s_waitcnt lgkmcnt(0)
	v_mfma_f32_16x16x32_bf16 v[156:159], v[156:159], v[78:81], 0
	v_mfma_f32_16x16x32_bf16 v[156:159], v[176:179], v[74:77], v[156:159]
	ds_read_b128 v[176:179], v148 offset:13184
	s_waitcnt lgkmcnt(0)
	v_mfma_f32_16x16x32_bf16 v[156:159], v[176:179], v[70:73], v[156:159]
	ds_read_b128 v[176:179], v148 offset:13248
	s_waitcnt lgkmcnt(0)
	v_mfma_f32_16x16x32_bf16 v[156:159], v[176:179], v[66:69], v[156:159]
	ds_read_b128 v[176:179], v149 offset:13056
	s_nop 6
	v_pk_mul_f32 v[158:159], v[98:99], v[158:159] op_sel_hi:[0,1]
	v_pk_mul_f32 v[156:157], v[98:99], v[156:157] op_sel_hi:[0,1]
	s_waitcnt lgkmcnt(0)
	s_nop 0
	v_mfma_f32_16x16x32_bf16 v[156:159], v[176:179], v[82:85], v[156:159]
	ds_read_b128 v[176:179], v149 offset:13120
	s_waitcnt lgkmcnt(0)
	v_mfma_f32_16x16x32_bf16 v[156:159], v[176:179], v[86:89], v[156:159]
	ds_read_b128 v[176:179], v149 offset:13184
	s_waitcnt lgkmcnt(0)
	v_mfma_f32_16x16x32_bf16 v[156:159], v[176:179], v[90:93], v[156:159]
	ds_read_b128 v[176:179], v149 offset:13248
	s_waitcnt lgkmcnt(0)
	v_mfma_f32_16x16x32_bf16 v[156:159], v[176:179], v[94:97], v[156:159]
	ds_read_b128 v[176:179], v148 offset:17472
	s_nop 6
	v_pk_mul_f32 v[112:113], v[100:101], v[158:159] op_sel_hi:[0,1]
	v_pk_mul_f32 v[156:157], v[100:101], v[156:157] op_sel_hi:[0,1]
	v_cvt_pk_bf16_f32 v156, v156, v157
	v_cvt_pk_bf16_f32 v157, v112, v113
	global_store_dwordx2 v[110:111], v[156:157], off offset:96
	ds_read_b128 v[156:159], v148 offset:17408
	s_waitcnt lgkmcnt(0)
	v_mfma_f32_16x16x32_bf16 v[156:159], v[156:159], v[78:81], 0
	v_mfma_f32_16x16x32_bf16 v[156:159], v[176:179], v[74:77], v[156:159]
	ds_read_b128 v[176:179], v148 offset:17536
	s_waitcnt lgkmcnt(0)
	v_mfma_f32_16x16x32_bf16 v[156:159], v[176:179], v[70:73], v[156:159]
	ds_read_b128 v[176:179], v148 offset:17600
	s_waitcnt lgkmcnt(0)
	v_mfma_f32_16x16x32_bf16 v[156:159], v[176:179], v[66:69], v[156:159]
	ds_read_b128 v[176:179], v149 offset:17408
	s_nop 6
	v_pk_mul_f32 v[158:159], v[98:99], v[158:159] op_sel_hi:[0,1]
	v_pk_mul_f32 v[156:157], v[98:99], v[156:157] op_sel_hi:[0,1]
	s_waitcnt lgkmcnt(0)
	s_nop 0
	v_mfma_f32_16x16x32_bf16 v[156:159], v[176:179], v[82:85], v[156:159]
	ds_read_b128 v[176:179], v149 offset:17472
	s_waitcnt lgkmcnt(0)
	v_mfma_f32_16x16x32_bf16 v[156:159], v[176:179], v[86:89], v[156:159]
	ds_read_b128 v[176:179], v149 offset:17536
	s_waitcnt lgkmcnt(0)
	v_mfma_f32_16x16x32_bf16 v[156:159], v[176:179], v[90:93], v[156:159]
	ds_read_b128 v[176:179], v149 offset:17600
	s_waitcnt lgkmcnt(0)
	v_mfma_f32_16x16x32_bf16 v[156:159], v[176:179], v[94:97], v[156:159]
	ds_read_b128 v[176:179], v148 offset:21824
	s_nop 6
	v_pk_mul_f32 v[112:113], v[100:101], v[158:159] op_sel_hi:[0,1]
	v_pk_mul_f32 v[156:157], v[100:101], v[156:157] op_sel_hi:[0,1]
	v_cvt_pk_bf16_f32 v156, v156, v157
	v_cvt_pk_bf16_f32 v157, v112, v113
	global_store_dwordx2 v[110:111], v[156:157], off offset:128
	ds_read_b128 v[156:159], v148 offset:21760
	s_waitcnt lgkmcnt(0)
	v_mfma_f32_16x16x32_bf16 v[156:159], v[156:159], v[78:81], 0
	v_mfma_f32_16x16x32_bf16 v[156:159], v[176:179], v[74:77], v[156:159]
	ds_read_b128 v[176:179], v148 offset:21888
	s_waitcnt lgkmcnt(0)
	v_mfma_f32_16x16x32_bf16 v[156:159], v[176:179], v[70:73], v[156:159]
	ds_read_b128 v[176:179], v148 offset:21952
	s_waitcnt lgkmcnt(0)
	v_mfma_f32_16x16x32_bf16 v[156:159], v[176:179], v[66:69], v[156:159]
	ds_read_b128 v[176:179], v149 offset:21760
	s_nop 6
	v_pk_mul_f32 v[158:159], v[98:99], v[158:159] op_sel_hi:[0,1]
	v_pk_mul_f32 v[156:157], v[98:99], v[156:157] op_sel_hi:[0,1]
	s_waitcnt lgkmcnt(0)
	s_nop 0
	v_mfma_f32_16x16x32_bf16 v[156:159], v[176:179], v[82:85], v[156:159]
	ds_read_b128 v[176:179], v149 offset:21824
	s_waitcnt lgkmcnt(0)
	v_mfma_f32_16x16x32_bf16 v[156:159], v[176:179], v[86:89], v[156:159]
	ds_read_b128 v[176:179], v149 offset:21888
	s_waitcnt lgkmcnt(0)
	v_mfma_f32_16x16x32_bf16 v[156:159], v[176:179], v[90:93], v[156:159]
	ds_read_b128 v[176:179], v149 offset:21952
	s_waitcnt lgkmcnt(0)
	v_mfma_f32_16x16x32_bf16 v[156:159], v[176:179], v[94:97], v[156:159]
	ds_read_b128 v[176:179], v148 offset:26176
	s_nop 6
	v_pk_mul_f32 v[112:113], v[100:101], v[158:159] op_sel_hi:[0,1]
	v_pk_mul_f32 v[156:157], v[100:101], v[156:157] op_sel_hi:[0,1]
	v_cvt_pk_bf16_f32 v156, v156, v157
	v_cvt_pk_bf16_f32 v157, v112, v113
	global_store_dwordx2 v[110:111], v[156:157], off offset:160
	ds_read_b128 v[156:159], v148 offset:26112
	s_waitcnt lgkmcnt(0)
	v_mfma_f32_16x16x32_bf16 v[156:159], v[156:159], v[78:81], 0
	v_mfma_f32_16x16x32_bf16 v[156:159], v[176:179], v[74:77], v[156:159]
	ds_read_b128 v[176:179], v148 offset:26240
	s_waitcnt lgkmcnt(0)
	v_mfma_f32_16x16x32_bf16 v[156:159], v[176:179], v[70:73], v[156:159]
	ds_read_b128 v[176:179], v148 offset:26304
	s_waitcnt lgkmcnt(0)
	v_mfma_f32_16x16x32_bf16 v[156:159], v[176:179], v[66:69], v[156:159]
	ds_read_b128 v[176:179], v149 offset:26112
	s_nop 6
	v_pk_mul_f32 v[158:159], v[98:99], v[158:159] op_sel_hi:[0,1]
	v_pk_mul_f32 v[156:157], v[98:99], v[156:157] op_sel_hi:[0,1]
	s_waitcnt lgkmcnt(0)
	s_nop 0
	v_mfma_f32_16x16x32_bf16 v[156:159], v[176:179], v[82:85], v[156:159]
	ds_read_b128 v[176:179], v149 offset:26176
	s_waitcnt lgkmcnt(0)
	v_mfma_f32_16x16x32_bf16 v[156:159], v[176:179], v[86:89], v[156:159]
	ds_read_b128 v[176:179], v149 offset:26240
	s_waitcnt lgkmcnt(0)
	v_mfma_f32_16x16x32_bf16 v[156:159], v[176:179], v[90:93], v[156:159]
	ds_read_b128 v[176:179], v149 offset:26304
	s_waitcnt lgkmcnt(0)
	v_mfma_f32_16x16x32_bf16 v[156:159], v[176:179], v[94:97], v[156:159]
	s_nop 7
	v_pk_mul_f32 v[112:113], v[100:101], v[158:159] op_sel_hi:[0,1]
	v_pk_mul_f32 v[156:157], v[100:101], v[156:157] op_sel_hi:[0,1]
	v_cvt_pk_bf16_f32 v156, v156, v157
	v_cvt_pk_bf16_f32 v157, v112, v113
	global_store_dwordx2 v[110:111], v[156:157], off offset:192
	ds_read_b128 v[156:159], v148 offset:30464
	s_waitcnt lgkmcnt(0)
	v_mfma_f32_16x16x32_bf16 v[78:81], v[156:159], v[78:81], 0
	ds_read_b128 v[156:159], v148 offset:30528
	s_waitcnt lgkmcnt(0)
	v_mfma_f32_16x16x32_bf16 v[74:77], v[156:159], v[74:77], v[78:81]
	s_nop 4
	ds_read_b128 v[78:81], v148 offset:30592
	s_waitcnt lgkmcnt(0)
	v_mfma_f32_16x16x32_bf16 v[70:73], v[78:81], v[70:73], v[74:77]
	s_nop 2
	ds_read_b128 v[74:77], v148 offset:30656
	s_waitcnt lgkmcnt(0)
	v_mfma_f32_16x16x32_bf16 v[66:69], v[74:77], v[66:69], v[70:73]
	s_nop 2
	ds_read_b128 v[70:73], v149 offset:30464
	s_nop 3
	v_pk_mul_f32 v[68:69], v[98:99], v[68:69] op_sel_hi:[0,1]
	v_pk_mul_f32 v[66:67], v[98:99], v[66:67] op_sel_hi:[0,1]
	s_waitcnt lgkmcnt(0)
	s_nop 0
	v_mfma_f32_16x16x32_bf16 v[66:69], v[70:73], v[82:85], v[66:69]
	ds_read_b128 v[70:73], v149 offset:30528
	s_waitcnt lgkmcnt(0)
	v_mfma_f32_16x16x32_bf16 v[66:69], v[70:73], v[86:89], v[66:69]
	ds_read_b128 v[70:73], v149 offset:30592
	s_waitcnt lgkmcnt(0)
	v_mfma_f32_16x16x32_bf16 v[66:69], v[70:73], v[90:93], v[66:69]
	ds_read_b128 v[70:73], v149 offset:30656
	s_waitcnt lgkmcnt(0)
	v_mfma_f32_16x16x32_bf16 v[66:69], v[70:73], v[94:97], v[66:69]
	s_nop 7
	v_pk_mul_f32 v[68:69], v[100:101], v[68:69] op_sel_hi:[0,1]
	v_pk_mul_f32 v[66:67], v[100:101], v[66:67] op_sel_hi:[0,1]
	v_cvt_pk_bf16_f32 v66, v66, v67
	v_cvt_pk_bf16_f32 v67, v68, v69
	global_store_dwordx2 v[110:111], v[66:67], off offset:224
	v_sub_f32_e32 v66, v154, v152
	v_mul_f32_e32 v82, 0x3fb8aa3b, v66
	ds_read_b128 v[78:81], v150
	ds_read_b128 v[74:77], v150 offset:64
	ds_read_b128 v[70:73], v150 offset:128
	ds_read_b128 v[66:69], v150 offset:192
	v_exp_f32_e32 v82, v82
	ds_read_b128 v[84:87], v151 offset:34816
	v_pk_mul_f32 v[4:5], v[4:5], v[82:83] op_sel_hi:[1,0]
	v_pk_mul_f32 v[2:3], v[2:3], v[82:83] op_sel_hi:[1,0]
	v_pk_mul_f32 v[8:9], v[8:9], v[82:83] op_sel_hi:[1,0]
	v_pk_mul_f32 v[6:7], v[6:7], v[82:83] op_sel_hi:[1,0]
	s_waitcnt lgkmcnt(0)
	v_mfma_f32_16x16x32_bf16 v[2:5], v[78:81], v[84:87], v[2:5]
	ds_read_b128 v[84:87], v151 offset:34880
	v_pk_mul_f32 v[12:13], v[12:13], v[82:83] op_sel_hi:[1,0]
	v_pk_mul_f32 v[10:11], v[10:11], v[82:83] op_sel_hi:[1,0]
	s_waitcnt lgkmcnt(0)
	v_mfma_f32_16x16x32_bf16 v[2:5], v[74:77], v[84:87], v[2:5]
	ds_read_b128 v[84:87], v151 offset:34944
	v_pk_mul_f32 v[16:17], v[16:17], v[82:83] op_sel_hi:[1,0]
	v_pk_mul_f32 v[14:15], v[14:15], v[82:83] op_sel_hi:[1,0]
	s_waitcnt lgkmcnt(0)
	v_mfma_f32_16x16x32_bf16 v[2:5], v[70:73], v[84:87], v[2:5]
	ds_read_b128 v[84:87], v151 offset:35008
	v_pk_mul_f32 v[20:21], v[20:21], v[82:83] op_sel_hi:[1,0]
	v_pk_mul_f32 v[18:19], v[18:19], v[82:83] op_sel_hi:[1,0]
	s_waitcnt lgkmcnt(0)
	v_mfma_f32_16x16x32_bf16 v[2:5], v[66:69], v[84:87], v[2:5]
	ds_read_b128 v[84:87], v151 offset:39168
	v_pk_mul_f32 v[24:25], v[24:25], v[82:83] op_sel_hi:[1,0]
	v_pk_mul_f32 v[22:23], v[22:23], v[82:83] op_sel_hi:[1,0]
	s_waitcnt lgkmcnt(0)
	v_mfma_f32_16x16x32_bf16 v[6:9], v[78:81], v[84:87], v[6:9]
	ds_read_b128 v[84:87], v151 offset:39232
	v_pk_mul_f32 v[28:29], v[28:29], v[82:83] op_sel_hi:[1,0]
	v_pk_mul_f32 v[26:27], v[26:27], v[82:83] op_sel_hi:[1,0]
	s_waitcnt lgkmcnt(0)
	v_mfma_f32_16x16x32_bf16 v[6:9], v[74:77], v[84:87], v[6:9]
	ds_read_b128 v[84:87], v151 offset:39296
	v_pk_mul_f32 v[32:33], v[32:33], v[82:83] op_sel_hi:[1,0]
	v_pk_mul_f32 v[30:31], v[30:31], v[82:83] op_sel_hi:[1,0]
	s_waitcnt lgkmcnt(0)
	v_mfma_f32_16x16x32_bf16 v[6:9], v[70:73], v[84:87], v[6:9]
	ds_read_b128 v[84:87], v151 offset:39360
	s_waitcnt lgkmcnt(0)
	v_mfma_f32_16x16x32_bf16 v[6:9], v[66:69], v[84:87], v[6:9]
	ds_read_b128 v[84:87], v151 offset:43520
	s_waitcnt lgkmcnt(0)
	v_mfma_f32_16x16x32_bf16 v[10:13], v[78:81], v[84:87], v[10:13]
	ds_read_b128 v[84:87], v151 offset:43584
	s_waitcnt lgkmcnt(0)
	v_mfma_f32_16x16x32_bf16 v[10:13], v[74:77], v[84:87], v[10:13]
	ds_read_b128 v[84:87], v151 offset:43648
	s_waitcnt lgkmcnt(0)
	v_mfma_f32_16x16x32_bf16 v[10:13], v[70:73], v[84:87], v[10:13]
	ds_read_b128 v[84:87], v151 offset:43712
	s_waitcnt lgkmcnt(0)
	v_mfma_f32_16x16x32_bf16 v[10:13], v[66:69], v[84:87], v[10:13]
	ds_read_b128 v[84:87], v151 offset:47872
	s_waitcnt lgkmcnt(0)
	v_mfma_f32_16x16x32_bf16 v[14:17], v[78:81], v[84:87], v[14:17]
	ds_read_b128 v[84:87], v151 offset:47936
	s_waitcnt lgkmcnt(0)
	v_mfma_f32_16x16x32_bf16 v[14:17], v[74:77], v[84:87], v[14:17]
	ds_read_b128 v[84:87], v151 offset:48000
	s_waitcnt lgkmcnt(0)
	v_mfma_f32_16x16x32_bf16 v[14:17], v[70:73], v[84:87], v[14:17]
	ds_read_b128 v[84:87], v151 offset:48064
	s_waitcnt lgkmcnt(0)
	v_mfma_f32_16x16x32_bf16 v[14:17], v[66:69], v[84:87], v[14:17]
	ds_read_b128 v[84:87], v151 offset:52224
	s_waitcnt lgkmcnt(0)
	v_mfma_f32_16x16x32_bf16 v[18:21], v[78:81], v[84:87], v[18:21]
	ds_read_b128 v[84:87], v151 offset:52288
	s_waitcnt lgkmcnt(0)
	v_mfma_f32_16x16x32_bf16 v[18:21], v[74:77], v[84:87], v[18:21]
	ds_read_b128 v[84:87], v151 offset:52352
	s_waitcnt lgkmcnt(0)
	v_mfma_f32_16x16x32_bf16 v[18:21], v[70:73], v[84:87], v[18:21]
	ds_read_b128 v[84:87], v151 offset:52416
	s_waitcnt lgkmcnt(0)
	v_mfma_f32_16x16x32_bf16 v[18:21], v[66:69], v[84:87], v[18:21]
	ds_read_b128 v[84:87], v151 offset:56576
	s_waitcnt lgkmcnt(0)
	v_mfma_f32_16x16x32_bf16 v[22:25], v[78:81], v[84:87], v[22:25]
	ds_read_b128 v[84:87], v151 offset:56640
	s_waitcnt lgkmcnt(0)
	v_mfma_f32_16x16x32_bf16 v[22:25], v[74:77], v[84:87], v[22:25]
	ds_read_b128 v[84:87], v151 offset:56704
	s_waitcnt lgkmcnt(0)
	v_mfma_f32_16x16x32_bf16 v[22:25], v[70:73], v[84:87], v[22:25]
	ds_read_b128 v[84:87], v151 offset:56768
	s_waitcnt lgkmcnt(0)
	v_mfma_f32_16x16x32_bf16 v[22:25], v[66:69], v[84:87], v[22:25]
	ds_read_b128 v[84:87], v151 offset:60928
	s_waitcnt lgkmcnt(0)
	v_mfma_f32_16x16x32_bf16 v[26:29], v[78:81], v[84:87], v[26:29]
	ds_read_b128 v[84:87], v151 offset:60992
	s_waitcnt lgkmcnt(0)
	v_mfma_f32_16x16x32_bf16 v[26:29], v[74:77], v[84:87], v[26:29]
	ds_read_b128 v[84:87], v151 offset:61056
	s_waitcnt lgkmcnt(0)
	v_mfma_f32_16x16x32_bf16 v[26:29], v[70:73], v[84:87], v[26:29]
	ds_read_b128 v[84:87], v151 offset:61120
	s_waitcnt lgkmcnt(0)
	v_mfma_f32_16x16x32_bf16 v[26:29], v[66:69], v[84:87], v[26:29]
	ds_read_b128 v[84:87], v151 offset:65280
	s_waitcnt lgkmcnt(0)
	v_mfma_f32_16x16x32_bf16 v[30:33], v[78:81], v[84:87], v[30:33]
	ds_read_b128 v[78:81], v151 offset:65344
	s_waitcnt lgkmcnt(0)
	v_mfma_f32_16x16x32_bf16 v[30:33], v[74:77], v[78:81], v[30:33]
	ds_read_b128 v[74:77], v151 offset:65408
	s_waitcnt lgkmcnt(0)
	v_mfma_f32_16x16x32_bf16 v[30:33], v[70:73], v[74:77], v[30:33]
	ds_read_b128 v[70:73], v151 offset:65472
	s_waitcnt lgkmcnt(0)
	v_mfma_f32_16x16x32_bf16 v[30:33], v[66:69], v[70:73], v[30:33]
	v_mov_b32_e32 v66, 0
	s_and_saveexec_b64 s[96:97], s[4:5]
	s_cbranch_execz .LBB0_695
	v_mov_b32_e32 v66, 0

.LBB0_1239:
	v_lshlrev_b64 v[152:153], 2, v[152:153]
	v_lshl_add_u64 v[158:159], s[10:11], 0, v[158:159]
	v_lshl_add_u64 v[154:155], v[156:157], 0, v[152:153]
	v_lshl_add_u64 v[152:153], v[158:159], 0, v[152:153]
	global_load_dwordx4 v[156:159], v[154:155], off offset:16
	global_load_dwordx4 v[176:179], v[154:155], off
	global_load_dwordx4 v[180:183], v[154:155], off offset:144
	global_load_dwordx4 v[184:187], v[154:155], off offset:128
	s_mov_b64 s[14:15], 0x10000
	v_add_co_u32_e32 v174, vcc, 0x10000, v154
	v_lshl_add_u64 v[172:173], v[154:155], 0, s[14:15]
	s_nop 0
	v_addc_co_u32_e32 v175, vcc, 0, v155, vcc
	s_mov_b64 s[14:15], 0x10080
	global_load_dwordx4 v[188:191], v[174:175], off
	global_load_dwordx4 v[192:195], v[172:173], off offset:16
	v_lshl_add_u64 v[172:173], v[154:155], 0, s[14:15]
	global_load_dwordx4 v[196:199], v[174:175], off offset:128
	global_load_dwordx4 v[230:233], v[172:173], off offset:16
	s_mov_b32 s14, 0x10000
	s_mov_b64 s[16:17], 0x20080
	s_mov_b32 s40, s37
	s_mov_b32 s39, s38
	s_waitcnt vmcnt(0)
	v_pk_fma_f32 v[138:139], v[138:139], v[102:103], v[156:157]
	v_pk_fma_f32 v[144:145], v[144:145], v[112:113], v[178:179]
	v_pk_fma_f32 v[126:127], v[126:127], v[98:99], v[180:181]
	v_pk_fma_f32 v[132:133], v[132:133], v[108:109], v[186:187]
	v_pk_fma_f32 v[130:131], v[130:131], v[106:107], v[184:185]
	global_store_dwordx4 v[152:153], v[130:133], off offset:128
	v_pk_fma_f32 v[128:129], v[128:129], v[100:101], v[182:183]
	v_pk_fma_f32 v[142:143], v[142:143], v[110:111], v[176:177]
	v_add_co_u32_e32 v130, vcc, s14, v152
	s_mov_b64 s[14:15], 0x20000
	s_nop 0
	v_addc_co_u32_e32 v131, vcc, 0, v153, vcc
	v_pk_fma_f32 v[120:121], v[120:121], v[108:109], v[198:199]
	v_pk_fma_f32 v[118:119], v[118:119], v[106:107], v[196:197]
	v_pk_fma_f32 v[122:123], v[122:123], v[102:103], v[192:193]
	v_pk_fma_f32 v[124:125], v[124:125], v[104:105], v[194:195]
	global_store_dwordx4 v[130:131], v[118:121], off offset:128
	v_pk_fma_f32 v[140:141], v[140:141], v[104:105], v[158:159]
	global_store_dwordx4 v[152:153], v[126:129], off offset:144
	v_lshl_add_u64 v[118:119], v[154:155], 0, s[14:15]
	s_mov_b32 s14, 0x20000
	v_pk_fma_f32 v[128:129], v[136:137], v[112:113], v[190:191]
	v_pk_fma_f32 v[126:127], v[134:135], v[110:111], v[188:189]
	global_store_dwordx4 v[130:131], v[122:125], off offset:16
	v_pk_fma_f32 v[114:115], v[114:115], v[98:99], v[230:231]
	v_pk_fma_f32 v[116:117], v[116:117], v[100:101], v[232:233]
	v_add_co_u32_e32 v122, vcc, s14, v154
	global_store_dwordx4 v[152:153], v[142:145], off
	global_store_dwordx4 v[152:153], v[138:141], off offset:16
	global_store_dwordx4 v[130:131], v[126:129], off
	global_store_dwordx4 v[130:131], v[114:117], off offset:144
	v_addc_co_u32_e32 v123, vcc, 0, v155, vcc
	global_load_dwordx4 v[114:117], v[122:123], off
	s_nop 0
	global_load_dwordx4 v[118:121], v[118:119], off offset:16
	v_lshl_add_u64 v[126:127], v[154:155], 0, s[16:17]
	s_mov_b64 s[16:17], 0x30000
	global_load_dwordx4 v[122:125], v[122:123], off offset:128
	s_nop 0
	global_load_dwordx4 v[126:129], v[126:127], off offset:16
	v_lshl_add_u64 v[134:135], v[154:155], 0, s[16:17]
	v_add_co_u32_e32 v138, vcc, s94, v154
	s_mov_b64 s[16:17], 0x30080
	s_nop 0
	v_addc_co_u32_e32 v139, vcc, 0, v155, vcc
	v_lshl_add_u64 v[142:143], v[154:155], 0, s[16:17]
	global_load_dwordx4 v[130:133], v[138:139], off
	s_nop 0
	global_load_dwordx4 v[134:137], v[134:135], off offset:16
	s_nop 0
	global_load_dwordx4 v[138:141], v[138:139], off offset:128
	s_nop 0
	global_load_dwordx4 v[142:145], v[142:143], off offset:16
	s_mov_b64 s[16:17], 0x80080
	s_waitcnt vmcnt(0)
	v_pk_fma_f32 v[94:95], v[94:95], v[110:111], v[114:115]
	v_add_co_u32_e32 v114, vcc, s14, v152
	v_pk_fma_f32 v[84:85], v[84:85], v[108:109], v[124:125]
	s_nop 0
	v_addc_co_u32_e32 v115, vcc, 0, v153, vcc
	v_pk_fma_f32 v[82:83], v[82:83], v[106:107], v[122:123]
	global_store_dwordx4 v[114:115], v[82:85], off offset:128
	s_mov_b64 s[14:15], 0x80000
	v_pk_fma_f32 v[78:79], v[78:79], v[98:99], v[126:127]
	v_add_co_u32_e32 v82, vcc, s94, v152
	v_pk_fma_f32 v[72:73], v[72:73], v[108:109], v[140:141]
	s_nop 0
	v_addc_co_u32_e32 v83, vcc, 0, v153, vcc
	v_pk_fma_f32 v[70:71], v[70:71], v[106:107], v[138:139]
	v_pk_fma_f32 v[80:81], v[80:81], v[100:101], v[128:129]
	v_pk_fma_f32 v[74:75], v[74:75], v[102:103], v[134:135]
	v_pk_fma_f32 v[76:77], v[76:77], v[104:105], v[136:137]
	global_store_dwordx4 v[82:83], v[70:73], off offset:128
	v_pk_fma_f32 v[96:97], v[96:97], v[112:113], v[116:117]
	v_pk_fma_f32 v[90:91], v[90:91], v[102:103], v[118:119]
	v_lshl_add_u64 v[70:71], v[154:155], 0, s[14:15]
	s_mov_b32 s14, 0x80000
	v_pk_fma_f32 v[92:93], v[92:93], v[104:105], v[120:121]
	global_store_dwordx4 v[114:115], v[78:81], off offset:144
	global_store_dwordx4 v[82:83], v[74:77], off offset:16
	v_pk_fma_f32 v[66:67], v[66:67], v[98:99], v[142:143]
	v_pk_fma_f32 v[80:81], v[88:89], v[112:113], v[132:133]
	v_pk_fma_f32 v[78:79], v[86:87], v[110:111], v[130:131]
	v_pk_fma_f32 v[68:69], v[68:69], v[100:101], v[144:145]
	v_add_co_u32_e32 v74, vcc, s14, v154
	global_store_dwordx4 v[114:115], v[94:97], off
	global_store_dwordx4 v[114:115], v[90:93], off offset:16
	global_store_dwordx4 v[82:83], v[78:81], off
	global_store_dwordx4 v[82:83], v[66:69], off offset:144
	s_cmp_lg_u32 s99, 0
	s_cbranch_scc1 .Lfd_half_done
	v_addc_co_u32_e32 v75, vcc, 0, v155, vcc
	global_load_dwordx4 v[66:69], v[74:75], off
	s_nop 0
	global_load_dwordx4 v[70:73], v[70:71], off offset:16
	v_lshl_add_u64 v[78:79], v[154:155], 0, s[16:17]
	s_mov_b64 s[16:17], 0x90000
	s_mov_b32 s15, 0x90000
	global_load_dwordx4 v[74:77], v[74:75], off offset:128
	s_nop 0
	global_load_dwordx4 v[78:81], v[78:79], off offset:16
	v_lshl_add_u64 v[86:87], v[154:155], 0, s[16:17]
	v_add_co_u32_e32 v90, vcc, s15, v154
	s_mov_b64 s[16:17], 0x90080
	s_nop 0
	v_addc_co_u32_e32 v91, vcc, 0, v155, vcc
	v_lshl_add_u64 v[94:95], v[154:155], 0, s[16:17]
	global_load_dwordx4 v[82:85], v[90:91], off
	s_nop 0
	global_load_dwordx4 v[86:89], v[86:87], off offset:16
	s_nop 0
	global_load_dwordx4 v[90:93], v[90:91], off offset:128
	s_nop 0
	global_load_dwordx4 v[94:97], v[94:95], off offset:16
	s_mov_b64 s[16:17], 0xa0080
	s_waitcnt vmcnt(0)
	v_pk_fma_f32 v[62:63], v[62:63], v[110:111], v[66:67]
	v_add_co_u32_e32 v66, vcc, s14, v152
	v_pk_fma_f32 v[64:65], v[64:65], v[112:113], v[68:69]
	s_nop 0
	v_addc_co_u32_e32 v67, vcc, 0, v153, vcc
	v_pk_fma_f32 v[52:53], v[52:53], v[108:109], v[76:77]
	v_pk_fma_f32 v[50:51], v[50:51], v[106:107], v[74:75]
	global_store_dwordx4 v[66:67], v[50:53], off offset:128
	v_pk_fma_f32 v[46:47], v[46:47], v[98:99], v[78:79]
	v_pk_fma_f32 v[48:49], v[48:49], v[100:101], v[80:81]
	v_add_co_u32_e32 v50, vcc, s15, v152
	v_pk_fma_f32 v[40:41], v[40:41], v[108:109], v[92:93]
	s_nop 0
	v_addc_co_u32_e32 v51, vcc, 0, v153, vcc
	v_pk_fma_f32 v[38:39], v[38:39], v[106:107], v[90:91]
	s_mov_b64 s[14:15], 0xa0000
	v_pk_fma_f32 v[42:43], v[42:43], v[102:103], v[86:87]
	v_pk_fma_f32 v[44:45], v[44:45], v[104:105], v[88:89]
	global_store_dwordx4 v[50:51], v[38:41], off offset:128
	v_pk_fma_f32 v[58:59], v[58:59], v[102:103], v[70:71]
	v_pk_fma_f32 v[60:61], v[60:61], v[104:105], v[72:73]
	v_lshl_add_u64 v[38:39], v[154:155], 0, s[14:15]
	s_mov_b32 s14, 0xa0000
	global_store_dwordx4 v[66:67], v[46:49], off offset:144
	global_store_dwordx4 v[50:51], v[42:45], off offset:16
	v_pk_fma_f32 v[34:35], v[34:35], v[98:99], v[94:95]
	v_pk_fma_f32 v[48:49], v[56:57], v[112:113], v[84:85]
	v_pk_fma_f32 v[46:47], v[54:55], v[110:111], v[82:83]
	v_pk_fma_f32 v[36:37], v[36:37], v[100:101], v[96:97]
	v_add_co_u32_e32 v42, vcc, s14, v154
	global_store_dwordx4 v[66:67], v[62:65], off
	global_store_dwordx4 v[66:67], v[58:61], off offset:16
	global_store_dwordx4 v[50:51], v[46:49], off
	global_store_dwordx4 v[50:51], v[34:37], off offset:144
	v_addc_co_u32_e32 v43, vcc, 0, v155, vcc
	global_load_dwordx4 v[34:37], v[42:43], off
	s_nop 0
	global_load_dwordx4 v[38:41], v[38:39], off offset:16
	v_lshl_add_u64 v[46:47], v[154:155], 0, s[16:17]
	s_mov_b64 s[16:17], 0xb0000
	s_mov_b32 s15, 0xb0000
	global_load_dwordx4 v[42:45], v[42:43], off offset:128
	s_nop 0
	global_load_dwordx4 v[46:49], v[46:47], off offset:16
	v_lshl_add_u64 v[54:55], v[154:155], 0, s[16:17]
	v_add_co_u32_e32 v58, vcc, s15, v154
	s_mov_b64 s[16:17], 0xb0080
	s_nop 0
	v_addc_co_u32_e32 v59, vcc, 0, v155, vcc
	v_lshl_add_u64 v[62:63], v[154:155], 0, s[16:17]
	global_load_dwordx4 v[50:53], v[58:59], off
	s_nop 0
	global_load_dwordx4 v[54:57], v[54:55], off offset:16
	s_nop 0
	global_load_dwordx4 v[58:61], v[58:59], off offset:128
	s_nop 0
	global_load_dwordx4 v[62:65], v[62:63], off offset:16
	s_mov_b64 s[16:17], s[8:9]
	s_waitcnt vmcnt(0)
	v_pk_fma_f32 v[30:31], v[30:31], v[110:111], v[34:35]
	v_add_co_u32_e32 v34, vcc, s14, v152
	v_pk_fma_f32 v[32:33], v[32:33], v[112:113], v[36:37]
	s_nop 0
	v_addc_co_u32_e32 v35, vcc, 0, v153, vcc
	v_pk_fma_f32 v[16:17], v[16:17], v[108:109], v[44:45]
	v_pk_fma_f32 v[14:15], v[14:15], v[106:107], v[42:43]
	global_store_dwordx4 v[34:35], v[14:17], off offset:128
	v_pk_fma_f32 v[10:11], v[10:11], v[98:99], v[46:47]
	v_pk_fma_f32 v[12:13], v[12:13], v[100:101], v[48:49]
	v_add_co_u32_e32 v14, vcc, s15, v152
	global_store_dwordx4 v[34:35], v[10:13], off offset:144
	s_nop 0
	v_addc_co_u32_e32 v15, vcc, 0, v153, vcc
	v_pk_fma_f32 v[12:13], v[24:25], v[112:113], v[52:53]
	v_pk_fma_f32 v[10:11], v[22:23], v[110:111], v[50:51]
	v_pk_fma_f32 v[26:27], v[26:27], v[102:103], v[38:39]
	v_pk_fma_f32 v[28:29], v[28:29], v[104:105], v[40:41]
	global_store_dwordx4 v[14:15], v[10:13], off
	v_pk_fma_f32 v[8:9], v[8:9], v[108:109], v[60:61]
	v_pk_fma_f32 v[6:7], v[6:7], v[106:107], v[58:59]
	v_pk_fma_f32 v[10:11], v[18:19], v[102:103], v[54:55]
	v_pk_fma_f32 v[12:13], v[20:21], v[104:105], v[56:57]
	v_pk_fma_f32 v[2:3], v[2:3], v[98:99], v[62:63]
	v_pk_fma_f32 v[4:5], v[4:5], v[100:101], v[64:65]
	s_and_b64 vcc, exec, s[4:5]
	s_mov_b64 s[14:15], s[6:7]
	global_store_dwordx4 v[34:35], v[30:33], off
	global_store_dwordx4 v[34:35], v[26:29], off offset:16
	global_store_dwordx4 v[14:15], v[10:13], off offset:16
	global_store_dwordx4 v[14:15], v[6:9], off offset:128
	global_store_dwordx4 v[14:15], v[2:5], off offset:144
	s_cbranch_vccnz .LBB0_1252
	s_branch .LBB0_1240
.Lfd_half_done:
	s_mov_b64 s[16:17], s[8:9]
	s_and_b64 vcc, exec, s[4:5]
	s_mov_b64 s[14:15], s[6:7]
	s_cbranch_vccnz .LBB0_1252
.LBB0_1240:
	s_add_i32 s36, s36, 1
	s_mul_i32 s4, s36, s35
	s_mul_hi_u32 s5, s36, s0
	s_add_i32 s5, s5, s4
	s_mul_i32 s4, s36, s0
	v_readlane_b32 s99, v255, 41
	s_cmp_eq_u32 s36, 1
	s_cselect_b32 s99, s99, 0
	s_lshr_b32 s98, s1, s99
	s_add_u32 s8, s4, s98
	s_addc_u32 s9, s5, s24
	v_cmp_gt_i64_e64 s[4:5], s[8:9], v[164:165]
	v_cmp_lt_i64_e64 s[6:7], s[8:9], v[166:167]
	s_and_b64 vcc, exec, s[4:5]
	s_cbranch_vccnz .LBB0_1242
	s_ashr_i32 s9, s8, 31
	s_lshr_b32 s9, s9, 29
	s_add_i32 s9, s8, s9
	s_ashr_i32 s18, s9, 3
	s_and_b32 s9, s9, -8
	s_sub_i32 s8, s8, s9
	s_cmp_lt_i32 s8, 0
	s_cselect_b32 s9, 49, 48
	s_mul_i32 s8, s9, s8
	s_add_i32 s8, s8, s18
	s_ashr_i32 s9, s8, 31
	s_lshr_b32 s9, s9, 28
	s_add_i32 s9, s8, s9
	s_ashr_i32 s18, s9, 4
	s_lshl_b32 s18, s18, 2
	s_sub_i32 s19, 0x60, s18
	s_min_i32 s19, s19, 4
	s_abs_i32 s20, s19
	v_cvt_f32_u32_e32 v2, s20
	s_sub_i32 s37, 0, s20
	s_and_b32 s9, s9, -16
	s_sub_i32 s8, s8, s9
	v_rcp_iflag_f32_e32 v2, v2
	s_abs_i32 s9, s8
	s_xor_b32 s21, s8, s19
	s_ashr_i32 s21, s21, 31
	v_mul_f32_e32 v2, 0x4f7ffffe, v2
	v_cvt_u32_f32_e32 v2, v2
	s_nop 0
	v_readfirstlane_b32 s38, v2
	s_mul_i32 s37, s37, s38
	s_mul_hi_u32 s37, s38, s37
	s_add_i32 s38, s38, s37
	s_mul_hi_u32 s37, s9, s38
	s_mul_i32 s38, s37, s20
	s_sub_i32 s9, s9, s38
	s_add_i32 s41, s37, 1
	s_sub_i32 s38, s9, s20
	s_cmp_ge_u32 s9, s20
	s_cselect_b32 s37, s41, s37
	s_cselect_b32 s9, s38, s9
	s_add_i32 s38, s37, 1
	s_cmp_ge_u32 s9, s20
	s_cselect_b32 s9, s38, s37
	s_xor_b32 s9, s9, s21
	s_sub_i32 s37, s9, s21
	s_mul_i32 s9, s37, s19
	s_sub_i32 s8, s8, s9
	s_add_i32 s38, s8, s18
.LBB0_1242:
	v_cndmask_b32_e64 v2, 0, 1, s[6:7]
	v_cmp_ne_u32_e64 s[8:9], 1, v2
	s_andn2_b64 vcc, exec, s[6:7]
	s_mov_b64 s[6:7], s[14:15]
	s_cbranch_vccnz .LBB0_1244
	s_mul_i32 s6, s38, 0x160000
	v_readlane_b32 s18, v254, 35
	s_mul_hi_i32 s7, s38, 0x160000
	v_readlane_b32 s19, v254, 36
	s_add_u32 s6, s18, s6
	s_addc_u32 s7, s19, s7
	v_readlane_b32 s98, v255, 41
	v_readlane_b32 s99, v254, 0
	s_and_b32 s99, s99, s98
	s_mul_i32 s99, s99, 0xb0000
	s_add_u32 s6, s6, s99
	s_addc_u32 s7, s7, 0

.LBB0_1246:
	v_readlane_b32 s99, v255, 41
	s_cmp_eq_u32 s36, 2
	s_cselect_b32 s99, s99, 0
	s_add_u32 s41, s16, 0x100
	v_mov_b32_e32 v2, 0
	s_addc_u32 s42, s17, 0
	s_mov_b32 s43, -2
	v_mov_b32_e32 v3, v2
	v_mov_b32_e32 v4, v2
	v_mov_b32_e32 v5, v2
	v_mov_b32_e32 v6, v2
	v_mov_b32_e32 v7, v2
	v_mov_b32_e32 v8, v2
	v_mov_b32_e32 v9, v2
	v_mov_b32_e32 v10, v2
	v_mov_b32_e32 v11, v2
	v_mov_b32_e32 v12, v2
	v_mov_b32_e32 v13, v2
	v_mov_b32_e32 v14, v2
	v_mov_b32_e32 v15, v2
	v_mov_b32_e32 v16, v2
	v_mov_b32_e32 v17, v2
	v_mov_b32_e32 v34, v2
	v_mov_b32_e32 v35, v2
	v_mov_b32_e32 v36, v2
	v_mov_b32_e32 v37, v2
	v_mov_b32_e32 v38, v2
	v_mov_b32_e32 v39, v2
	v_mov_b32_e32 v40, v2
	v_mov_b32_e32 v41, v2
	v_mov_b32_e32 v46, v2
	v_mov_b32_e32 v47, v2
	v_mov_b32_e32 v48, v2
	v_mov_b32_e32 v49, v2
	v_mov_b32_e32 v50, v2
	v_mov_b32_e32 v51, v2
	v_mov_b32_e32 v52, v2
	v_mov_b32_e32 v53, v2
	v_mov_b32_e32 v18, v2
	v_mov_b32_e32 v19, v2
	v_mov_b32_e32 v20, v2
	v_mov_b32_e32 v21, v2
	v_mov_b32_e32 v22, v2
	v_mov_b32_e32 v23, v2
	v_mov_b32_e32 v24, v2
	v_mov_b32_e32 v25, v2
	v_mov_b32_e32 v26, v2
	v_mov_b32_e32 v27, v2
	v_mov_b32_e32 v28, v2
	v_mov_b32_e32 v29, v2
	v_mov_b32_e32 v30, v2
	v_mov_b32_e32 v31, v2
	v_mov_b32_e32 v32, v2
	v_mov_b32_e32 v33, v2
	v_mov_b32_e32 v42, v2
	v_mov_b32_e32 v43, v2
	v_mov_b32_e32 v44, v2
	v_mov_b32_e32 v45, v2
	v_mov_b32_e32 v54, v2
	v_mov_b32_e32 v55, v2
	v_mov_b32_e32 v56, v2
	v_mov_b32_e32 v57, v2
	v_mov_b32_e32 v58, v2
	v_mov_b32_e32 v59, v2
	v_mov_b32_e32 v60, v2
	v_mov_b32_e32 v61, v2
	v_mov_b32_e32 v62, v2
	v_mov_b32_e32 v63, v2
	v_mov_b32_e32 v64, v2
	v_mov_b32_e32 v65, v2
	v_mov_b32_e32 v66, v2
	v_mov_b32_e32 v67, v2
	v_mov_b32_e32 v68, v2
	v_mov_b32_e32 v69, v2
	v_mov_b32_e32 v70, v2
	v_mov_b32_e32 v71, v2
	v_mov_b32_e32 v72, v2
	v_mov_b32_e32 v73, v2
	v_mov_b32_e32 v78, v2
	v_mov_b32_e32 v79, v2
	v_mov_b32_e32 v80, v2
	v_mov_b32_e32 v81, v2
	v_mov_b32_e32 v82, v2
	v_mov_b32_e32 v83, v2
	v_mov_b32_e32 v84, v2
	v_mov_b32_e32 v85, v2
	v_mov_b32_e32 v114, v2
	v_mov_b32_e32 v115, v2
	v_mov_b32_e32 v116, v2
	v_mov_b32_e32 v117, v2
	v_mov_b32_e32 v118, v2
	v_mov_b32_e32 v119, v2
	v_mov_b32_e32 v120, v2
	v_mov_b32_e32 v121, v2
	v_mov_b32_e32 v126, v2
	v_mov_b32_e32 v127, v2
	v_mov_b32_e32 v128, v2
	v_mov_b32_e32 v129, v2
	v_mov_b32_e32 v130, v2
	v_mov_b32_e32 v131, v2
	v_mov_b32_e32 v132, v2
	v_mov_b32_e32 v133, v2
	v_mov_b32_e32 v74, v2
	v_mov_b32_e32 v75, v2
	v_mov_b32_e32 v76, v2
	v_mov_b32_e32 v77, v2
	v_mov_b32_e32 v86, v2
	v_mov_b32_e32 v87, v2
	v_mov_b32_e32 v88, v2
	v_mov_b32_e32 v89, v2
	v_mov_b32_e32 v90, v2
	v_mov_b32_e32 v91, v2
	v_mov_b32_e32 v92, v2
	v_mov_b32_e32 v93, v2
	v_mov_b32_e32 v94, v2
	v_mov_b32_e32 v95, v2
	v_mov_b32_e32 v96, v2
	v_mov_b32_e32 v97, v2
	v_mov_b32_e32 v122, v2
	v_mov_b32_e32 v123, v2
	v_mov_b32_e32 v124, v2
	v_mov_b32_e32 v125, v2
	v_mov_b32_e32 v134, v2
	v_mov_b32_e32 v135, v2
	v_mov_b32_e32 v136, v2
	v_mov_b32_e32 v137, v2
	v_mov_b32_e32 v138, v2
	v_mov_b32_e32 v139, v2
	v_mov_b32_e32 v140, v2
	v_mov_b32_e32 v141, v2
	v_mov_b32_e32 v142, v2
	v_mov_b32_e32 v143, v2
	v_mov_b32_e32 v144, v2
	v_mov_b32_e32 v145, v2
.LBB0_1247:
	s_add_u32 s16, s14, 0x100
	s_addc_u32 s17, s15, 0
	s_add_i32 s44, 0, 0x10000
	v_add_u32_e32 v110, s44, v160
	ds_read_b128 v[98:101], v110
	ds_read_b128 v[102:105], v110 offset:1024
	ds_read_b128 v[106:109], v110 offset:2048
	ds_read_b128 v[110:113], v110 offset:3072
	s_cmp_eq_u32 s43, 40
	s_cselect_b32 s21, s7, s17
	s_cselect_b32 s20, s6, s16
	s_cselect_b32 s19, s9, s42
	s_cselect_b32 s18, s8, s41
	v_lshl_add_u64 v[172:173], s[14:15], 0, v[150:151]
	s_add_i32 m0, s25, 0xc000
	ds_read_b128 v[152:155], v161
	ds_read_b128 v[156:159], v161 offset:1024
	ds_read_b128 v[176:179], v161 offset:2048
	ds_read_b128 v[180:183], v161 offset:3072
	ds_read_b128 v[184:187], v161 offset:4096
	ds_read_b128 v[188:191], v161 offset:5120
	ds_read_b128 v[192:195], v161 offset:6144
	ds_read_b128 v[196:199], v161 offset:7168
	global_load_lds_dwordx4 v[172:173], off
	v_lshl_add_u64 v[172:173], s[14:15], 0, v[148:149]
	s_add_i32 m0, s25, 0xe000
	s_nop 0
	global_load_lds_dwordx4 v[172:173], off
	s_waitcnt lgkmcnt(8)
	s_barrier
	s_waitcnt lgkmcnt(0)
	s_setprio 1
	s_waitcnt lgkmcnt(0)
	v_mfma_f32_16x16x32_bf16 v[142:145], v[98:101], v[152:155], v[142:145]
	v_mfma_f32_16x16x32_bf16 v[138:141], v[106:109], v[152:155], v[138:141]
	v_mfma_f32_16x16x32_bf16 v[134:137], v[98:101], v[176:179], v[134:137]
	v_mfma_f32_16x16x32_bf16 v[122:125], v[106:109], v[176:179], v[122:125]
	v_mfma_f32_16x16x32_bf16 v[94:97], v[98:101], v[184:187], v[94:97]
	v_mfma_f32_16x16x32_bf16 v[90:93], v[106:109], v[184:187], v[90:93]
	v_mfma_f32_16x16x32_bf16 v[86:89], v[98:101], v[192:195], v[86:89]
	v_mfma_f32_16x16x32_bf16 v[74:77], v[106:109], v[192:195], v[74:77]
	v_mfma_f32_16x16x32_bf16 v[142:145], v[102:105], v[156:159], v[142:145]
	v_mfma_f32_16x16x32_bf16 v[138:141], v[110:113], v[156:159], v[138:141]
	v_mfma_f32_16x16x32_bf16 v[134:137], v[102:105], v[180:183], v[134:137]
	v_mfma_f32_16x16x32_bf16 v[122:125], v[110:113], v[180:183], v[122:125]
	v_mfma_f32_16x16x32_bf16 v[94:97], v[102:105], v[188:191], v[94:97]
	v_mfma_f32_16x16x32_bf16 v[90:93], v[110:113], v[188:191], v[90:93]
	v_mfma_f32_16x16x32_bf16 v[86:89], v[102:105], v[196:199], v[86:89]
	v_mfma_f32_16x16x32_bf16 v[74:77], v[110:113], v[196:199], v[74:77]
	s_setprio 0
	s_barrier
	s_add_i32 s45, 0, 0x14000
	s_add_i32 s14, s44, s23
	v_add_u32_e32 v169, s45, v160
	v_lshl_add_u64 v[172:173], s[18:19], 0, v[0:1]
	s_mov_b32 m0, s14
	ds_read_b128 v[230:233], v169
	ds_read_b128 v[234:237], v169 offset:1024
	ds_read_b128 v[238:241], v169 offset:2048
	ds_read_b128 v[242:245], v169 offset:3072
	global_load_lds_dwordx4 v[172:173], off
	v_lshl_add_u64 v[174:175], s[18:19], 0, v[146:147]
	s_add_i32 m0, s14, 0x2000
	s_nop 0
	global_load_lds_dwordx4 v[174:175], off
	s_barrier
	s_waitcnt lgkmcnt(0)
	s_setprio 1
	s_waitcnt lgkmcnt(0)
	v_mfma_f32_16x16x32_bf16 v[130:133], v[230:233], v[152:155], v[130:133]
	v_mfma_f32_16x16x32_bf16 v[126:129], v[238:241], v[152:155], v[126:129]
	v_mfma_f32_16x16x32_bf16 v[118:121], v[230:233], v[176:179], v[118:121]
	v_mfma_f32_16x16x32_bf16 v[114:117], v[238:241], v[176:179], v[114:117]
	v_mfma_f32_16x16x32_bf16 v[82:85], v[230:233], v[184:187], v[82:85]
	v_mfma_f32_16x16x32_bf16 v[78:81], v[238:241], v[184:187], v[78:81]
	v_mfma_f32_16x16x32_bf16 v[70:73], v[230:233], v[192:195], v[70:73]
	v_mfma_f32_16x16x32_bf16 v[66:69], v[238:241], v[192:195], v[66:69]
	v_mfma_f32_16x16x32_bf16 v[130:133], v[234:237], v[156:159], v[130:133]
	v_mfma_f32_16x16x32_bf16 v[126:129], v[242:245], v[156:159], v[126:129]
	v_mfma_f32_16x16x32_bf16 v[118:121], v[234:237], v[180:183], v[118:121]
	v_mfma_f32_16x16x32_bf16 v[114:117], v[242:245], v[180:183], v[114:117]
	v_mfma_f32_16x16x32_bf16 v[82:85], v[234:237], v[188:191], v[82:85]
	v_mfma_f32_16x16x32_bf16 v[78:81], v[242:245], v[188:191], v[78:81]
	v_mfma_f32_16x16x32_bf16 v[70:73], v[234:237], v[196:199], v[70:73]
	v_mfma_f32_16x16x32_bf16 v[66:69], v[242:245], v[196:199], v[66:69]
	s_setprio 0
	s_mov_b32 m0, s25
	v_lshl_add_u64 v[200:201], s[20:21], 0, v[0:1]
	s_barrier
	ds_read_b128 v[152:155], v161 offset:16384
	ds_read_b128 v[156:159], v161 offset:17408
	ds_read_b128 v[176:179], v161 offset:18432
	ds_read_b128 v[180:183], v161 offset:19456
	ds_read_b128 v[184:187], v161 offset:20480
	ds_read_b128 v[188:191], v161 offset:21504
	ds_read_b128 v[192:195], v161 offset:22528
	ds_read_b128 v[196:199], v161 offset:23552
	global_load_lds_dwordx4 v[200:201], off
	v_lshl_add_u64 v[210:211], s[20:21], 0, v[146:147]
	s_mov_b32 m0, s26
	s_nop 0
	global_load_lds_dwordx4 v[210:211], off
	s_barrier
	s_waitcnt lgkmcnt(0)
	s_setprio 1
	s_waitcnt lgkmcnt(0)
	s_cmp_lg_u32 s99, 0
	s_cbranch_scc1 .Lfd_skip3
	v_mfma_f32_16x16x32_bf16 v[62:65], v[98:101], v[152:155], v[62:65]
	v_mfma_f32_16x16x32_bf16 v[58:61], v[106:109], v[152:155], v[58:61]
	v_mfma_f32_16x16x32_bf16 v[54:57], v[98:101], v[176:179], v[54:57]
	v_mfma_f32_16x16x32_bf16 v[42:45], v[106:109], v[176:179], v[42:45]
	v_mfma_f32_16x16x32_bf16 v[30:33], v[98:101], v[184:187], v[30:33]
	v_mfma_f32_16x16x32_bf16 v[26:29], v[106:109], v[184:187], v[26:29]
	v_mfma_f32_16x16x32_bf16 v[22:25], v[98:101], v[192:195], v[22:25]
	v_mfma_f32_16x16x32_bf16 v[18:21], v[106:109], v[192:195], v[18:21]
	v_mfma_f32_16x16x32_bf16 v[62:65], v[102:105], v[156:159], v[62:65]
	v_mfma_f32_16x16x32_bf16 v[58:61], v[110:113], v[156:159], v[58:61]
	v_mfma_f32_16x16x32_bf16 v[54:57], v[102:105], v[180:183], v[54:57]
	v_mfma_f32_16x16x32_bf16 v[42:45], v[110:113], v[180:183], v[42:45]
	v_mfma_f32_16x16x32_bf16 v[30:33], v[102:105], v[188:191], v[30:33]
	v_mfma_f32_16x16x32_bf16 v[26:29], v[110:113], v[188:191], v[26:29]
	v_mfma_f32_16x16x32_bf16 v[22:25], v[102:105], v[196:199], v[22:25]
	v_mfma_f32_16x16x32_bf16 v[18:21], v[110:113], v[196:199], v[18:21]
.Lfd_skip3:
	s_setprio 0
	s_barrier
	s_add_u32 s14, s18, 0xb0000
	s_addc_u32 s15, s19, 0
	s_add_i32 s44, s45, s23
	v_lshl_add_u64 v[98:99], s[14:15], 0, v[0:1]
	s_mov_b32 m0, s44
	s_nop 0
	global_load_lds_dwordx4 v[98:99], off
	v_lshl_add_u64 v[98:99], s[14:15], 0, v[146:147]
	s_add_i32 m0, s44, 0x2000
	s_nop 0
	global_load_lds_dwordx4 v[98:99], off
	s_waitcnt vmcnt(6)
	s_barrier
	s_setprio 1
	s_cmp_lg_u32 s99, 0
	s_cbranch_scc1 .Lfd_skip4
	v_mfma_f32_16x16x32_bf16 v[50:53], v[230:233], v[152:155], v[50:53]
	v_mfma_f32_16x16x32_bf16 v[46:49], v[238:241], v[152:155], v[46:49]
	v_mfma_f32_16x16x32_bf16 v[38:41], v[230:233], v[176:179], v[38:41]
	v_mfma_f32_16x16x32_bf16 v[34:37], v[238:241], v[176:179], v[34:37]
	v_mfma_f32_16x16x32_bf16 v[14:17], v[230:233], v[184:187], v[14:17]
	v_mfma_f32_16x16x32_bf16 v[10:13], v[238:241], v[184:187], v[10:13]
	v_mfma_f32_16x16x32_bf16 v[6:9], v[230:233], v[192:195], v[6:9]
	v_mfma_f32_16x16x32_bf16 v[2:5], v[238:241], v[192:195], v[2:5]
	v_mfma_f32_16x16x32_bf16 v[50:53], v[234:237], v[156:159], v[50:53]
	v_mfma_f32_16x16x32_bf16 v[46:49], v[242:245], v[156:159], v[46:49]
	v_mfma_f32_16x16x32_bf16 v[38:41], v[234:237], v[180:183], v[38:41]
	v_mfma_f32_16x16x32_bf16 v[34:37], v[242:245], v[180:183], v[34:37]
	v_mfma_f32_16x16x32_bf16 v[14:17], v[234:237], v[188:191], v[14:17]
	v_mfma_f32_16x16x32_bf16 v[10:13], v[242:245], v[188:191], v[10:13]
	v_mfma_f32_16x16x32_bf16 v[6:9], v[234:237], v[196:199], v[6:9]
	v_mfma_f32_16x16x32_bf16 v[2:5], v[242:245], v[196:199], v[2:5]
.Lfd_skip4:
	s_setprio 0
	s_add_i32 s44, 0, 0x18000
	v_add_u32_e32 v110, s44, v160
	s_barrier
	ds_read_b128 v[98:101], v110
	ds_read_b128 v[102:105], v110 offset:1024
	ds_read_b128 v[106:109], v110 offset:2048
	ds_read_b128 v[110:113], v110 offset:3072
	s_add_u32 s14, s20, 0xb0000
	s_addc_u32 s15, s21, 0
	s_mov_b32 m0, s27
	v_lshl_add_u64 v[230:231], s[14:15], 0, v[0:1]
	ds_read_b128 v[152:155], v161 offset:32768
	ds_read_b128 v[156:159], v161 offset:33792
	ds_read_b128 v[176:179], v161 offset:34816
	ds_read_b128 v[180:183], v161 offset:35840
	ds_read_b128 v[184:187], v161 offset:36864
	ds_read_b128 v[188:191], v161 offset:37888
	ds_read_b128 v[192:195], v161 offset:38912
	ds_read_b128 v[196:199], v161 offset:39936
	global_load_lds_dwordx4 v[230:231], off
	v_lshl_add_u64 v[230:231], s[14:15], 0, v[146:147]
	s_mov_b32 m0, s28
	s_nop 0
	global_load_lds_dwordx4 v[230:231], off
	s_waitcnt lgkmcnt(8)
	s_barrier
	s_waitcnt lgkmcnt(0)
	s_setprio 1
	s_waitcnt lgkmcnt(0)
	v_mfma_f32_16x16x32_bf16 v[142:145], v[98:101], v[152:155], v[142:145]
	v_mfma_f32_16x16x32_bf16 v[138:141], v[106:109], v[152:155], v[138:141]
	v_mfma_f32_16x16x32_bf16 v[134:137], v[98:101], v[176:179], v[134:137]
	v_mfma_f32_16x16x32_bf16 v[122:125], v[106:109], v[176:179], v[122:125]
	v_mfma_f32_16x16x32_bf16 v[94:97], v[98:101], v[184:187], v[94:97]
	v_mfma_f32_16x16x32_bf16 v[90:93], v[106:109], v[184:187], v[90:93]
	v_mfma_f32_16x16x32_bf16 v[86:89], v[98:101], v[192:195], v[86:89]
	v_mfma_f32_16x16x32_bf16 v[74:77], v[106:109], v[192:195], v[74:77]
	v_mfma_f32_16x16x32_bf16 v[142:145], v[102:105], v[156:159], v[142:145]
	v_mfma_f32_16x16x32_bf16 v[138:141], v[110:113], v[156:159], v[138:141]
	v_mfma_f32_16x16x32_bf16 v[134:137], v[102:105], v[180:183], v[134:137]
	v_mfma_f32_16x16x32_bf16 v[122:125], v[110:113], v[180:183], v[122:125]
	v_mfma_f32_16x16x32_bf16 v[94:97], v[102:105], v[188:191], v[94:97]
	v_mfma_f32_16x16x32_bf16 v[90:93], v[110:113], v[188:191], v[90:93]
	v_mfma_f32_16x16x32_bf16 v[86:89], v[102:105], v[196:199], v[86:89]
	v_mfma_f32_16x16x32_bf16 v[74:77], v[110:113], v[196:199], v[74:77]
	s_setprio 0
	s_barrier
	s_add_i32 s20, 0, 0x1c000
	s_add_i32 s14, s44, s23
	v_add_u32_e32 v169, s20, v160
	v_lshl_add_u64 v[172:173], v[172:173], 0, s[92:93]
	s_mov_b32 m0, s14
	ds_read_b128 v[230:233], v169
	ds_read_b128 v[234:237], v169 offset:1024
	ds_read_b128 v[238:241], v169 offset:2048
	ds_read_b128 v[242:245], v169 offset:3072
	global_load_lds_dwordx4 v[172:173], off
	v_lshl_add_u64 v[172:173], v[174:175], 0, s[92:93]
	s_add_i32 m0, s14, 0x2000
	s_nop 0
	global_load_lds_dwordx4 v[172:173], off
	s_barrier
	s_waitcnt lgkmcnt(0)
	s_setprio 1
	s_waitcnt lgkmcnt(0)
	v_mfma_f32_16x16x32_bf16 v[130:133], v[230:233], v[152:155], v[130:133]
	v_mfma_f32_16x16x32_bf16 v[126:129], v[238:241], v[152:155], v[126:129]
	v_mfma_f32_16x16x32_bf16 v[118:121], v[230:233], v[176:179], v[118:121]
	v_mfma_f32_16x16x32_bf16 v[114:117], v[238:241], v[176:179], v[114:117]
	v_mfma_f32_16x16x32_bf16 v[82:85], v[230:233], v[184:187], v[82:85]
	v_mfma_f32_16x16x32_bf16 v[78:81], v[238:241], v[184:187], v[78:81]
	v_mfma_f32_16x16x32_bf16 v[70:73], v[230:233], v[192:195], v[70:73]
	v_mfma_f32_16x16x32_bf16 v[66:69], v[238:241], v[192:195], v[66:69]
	v_mfma_f32_16x16x32_bf16 v[130:133], v[234:237], v[156:159], v[130:133]
	v_mfma_f32_16x16x32_bf16 v[126:129], v[242:245], v[156:159], v[126:129]
	v_mfma_f32_16x16x32_bf16 v[118:121], v[234:237], v[180:183], v[118:121]
	v_mfma_f32_16x16x32_bf16 v[114:117], v[242:245], v[180:183], v[114:117]
	v_mfma_f32_16x16x32_bf16 v[82:85], v[234:237], v[188:191], v[82:85]
	v_mfma_f32_16x16x32_bf16 v[78:81], v[242:245], v[188:191], v[78:81]
	v_mfma_f32_16x16x32_bf16 v[70:73], v[234:237], v[196:199], v[70:73]
	v_mfma_f32_16x16x32_bf16 v[66:69], v[242:245], v[196:199], v[66:69]
	s_setprio 0
	s_mov_b32 m0, s31
	v_lshl_add_u64 v[172:173], v[200:201], 0, s[92:93]
	s_barrier
	ds_read_b128 v[152:155], v161 offset:49152
	ds_read_b128 v[156:159], v161 offset:50176
	ds_read_b128 v[176:179], v161 offset:51200
	ds_read_b128 v[180:183], v161 offset:52224
	ds_read_b128 v[184:187], v161 offset:53248
	ds_read_b128 v[188:191], v161 offset:54272
	ds_read_b128 v[192:195], v161 offset:55296
	ds_read_b128 v[196:199], v161 offset:56320
	global_load_lds_dwordx4 v[172:173], off
	v_lshl_add_u64 v[172:173], v[210:211], 0, s[92:93]
	s_mov_b32 m0, s34
	s_nop 0
	global_load_lds_dwordx4 v[172:173], off
	s_barrier
	s_waitcnt lgkmcnt(0)
	s_setprio 1
	s_waitcnt lgkmcnt(0)
	s_cmp_lg_u32 s99, 0
	s_cbranch_scc1 .Lfd_skip7
	v_mfma_f32_16x16x32_bf16 v[62:65], v[98:101], v[152:155], v[62:65]
	v_mfma_f32_16x16x32_bf16 v[58:61], v[106:109], v[152:155], v[58:61]
	v_mfma_f32_16x16x32_bf16 v[54:57], v[98:101], v[176:179], v[54:57]
	v_mfma_f32_16x16x32_bf16 v[42:45], v[106:109], v[176:179], v[42:45]
	v_mfma_f32_16x16x32_bf16 v[30:33], v[98:101], v[184:187], v[30:33]
	v_mfma_f32_16x16x32_bf16 v[26:29], v[106:109], v[184:187], v[26:29]
	v_mfma_f32_16x16x32_bf16 v[22:25], v[98:101], v[192:195], v[22:25]
	v_mfma_f32_16x16x32_bf16 v[18:21], v[106:109], v[192:195], v[18:21]
	v_mfma_f32_16x16x32_bf16 v[62:65], v[102:105], v[156:159], v[62:65]
	v_mfma_f32_16x16x32_bf16 v[58:61], v[110:113], v[156:159], v[58:61]
	v_mfma_f32_16x16x32_bf16 v[54:57], v[102:105], v[180:183], v[54:57]
	v_mfma_f32_16x16x32_bf16 v[42:45], v[110:113], v[180:183], v[42:45]
	v_mfma_f32_16x16x32_bf16 v[30:33], v[102:105], v[188:191], v[30:33]
	v_mfma_f32_16x16x32_bf16 v[26:29], v[110:113], v[188:191], v[26:29]
	v_mfma_f32_16x16x32_bf16 v[22:25], v[102:105], v[196:199], v[22:25]
	v_mfma_f32_16x16x32_bf16 v[18:21], v[110:113], v[196:199], v[18:21]
.Lfd_skip7:
	s_setprio 0
	s_barrier
	s_add_u32 s14, s18, 0xb0080
	s_addc_u32 s15, s19, 0
	s_add_i32 s18, s20, s23
	v_lshl_add_u64 v[98:99], s[14:15], 0, v[0:1]
	s_mov_b32 m0, s18
	s_nop 0
	global_load_lds_dwordx4 v[98:99], off
	v_lshl_add_u64 v[98:99], s[14:15], 0, v[146:147]
	s_add_i32 m0, s18, 0x2000
	s_nop 0
	global_load_lds_dwordx4 v[98:99], off
	s_waitcnt vmcnt(6)
	s_barrier
	s_setprio 1
	s_cmp_lg_u32 s99, 0
	s_cbranch_scc1 .Lfd_skip8
	v_mfma_f32_16x16x32_bf16 v[50:53], v[230:233], v[152:155], v[50:53]
	v_mfma_f32_16x16x32_bf16 v[46:49], v[238:241], v[152:155], v[46:49]
	v_mfma_f32_16x16x32_bf16 v[38:41], v[230:233], v[176:179], v[38:41]
	v_mfma_f32_16x16x32_bf16 v[34:37], v[238:241], v[176:179], v[34:37]
	v_mfma_f32_16x16x32_bf16 v[14:17], v[230:233], v[184:187], v[14:17]
	v_mfma_f32_16x16x32_bf16 v[10:13], v[238:241], v[184:187], v[10:13]
	v_mfma_f32_16x16x32_bf16 v[6:9], v[230:233], v[192:195], v[6:9]
	v_mfma_f32_16x16x32_bf16 v[2:5], v[238:241], v[192:195], v[2:5]
	v_mfma_f32_16x16x32_bf16 v[50:53], v[234:237], v[156:159], v[50:53]
	v_mfma_f32_16x16x32_bf16 v[46:49], v[242:245], v[156:159], v[46:49]
	v_mfma_f32_16x16x32_bf16 v[38:41], v[234:237], v[180:183], v[38:41]
	v_mfma_f32_16x16x32_bf16 v[34:37], v[242:245], v[180:183], v[34:37]
	v_mfma_f32_16x16x32_bf16 v[14:17], v[234:237], v[188:191], v[14:17]
	v_mfma_f32_16x16x32_bf16 v[10:13], v[242:245], v[188:191], v[10:13]
	v_mfma_f32_16x16x32_bf16 v[6:9], v[234:237], v[196:199], v[6:9]
	v_mfma_f32_16x16x32_bf16 v[2:5], v[242:245], v[196:199], v[2:5]
.Lfd_skip8:
	s_setprio 0
	s_add_i32 s43, s43, 2
	s_add_u32 s41, s41, 0x100
	s_addc_u32 s42, s42, 0
	s_cmp_gt_u32 s43, 41
	s_mov_b64 s[14:15], s[16:17]
	s_barrier
	s_cbranch_scc0 .LBB0_1247
	v_mov_b32_e32 v154, v163
	s_lshl_b32 s14, s39, 8
	v_readlane_b32 s98, v254, 0
	s_and_b32 s98, s98, s99
	s_lshl_b32 s98, s98, 7
	s_add_i32 s14, s14, s98
	v_ashrrev_i32_e32 v99, 2, v154
	v_and_b32_e32 v99, 0xffffffc0, v99
	v_add_u32_e32 v155, s14, v99
	s_addk_i32 s14, 0xe000
	s_lshr_b32 s14, s14, 11
	s_lshl_b32 s15, s40, 8
	v_lshrrev_b32_e32 v99, 1, v154
	s_add_i32 s16, s14, 1
	v_and_b32_e32 v98, 0xc0, v154
	v_and_b32_e32 v99, 24, v99
	s_cmp_gt_i32 s39, 31
	v_or3_b32 v152, v98, s15, v99
	s_cselect_b64 s[14:15], -1, 0
	s_and_b64 vcc, s[14:15], exec
	s_cselect_b32 s14, s16, 0
	s_mul_hi_u32 s15, s14, 0x6000
	s_mulk_i32 s14, 0x6000
	s_add_u32 s14, s29, s14
	s_addc_u32 s15, s30, s15
	v_ashrrev_i32_e32 v153, 31, v152
	v_lshl_add_u64 v[106:107], v[152:153], 2, s[14:15]
	global_load_dwordx4 v[102:105], v[106:107], off offset:16
	global_load_dwordx4 v[110:113], v[106:107], off
	global_load_dwordx4 v[98:101], v[106:107], off offset:144
	s_nop 0
	global_load_dwordx4 v[106:109], v[106:107], off offset:128
	v_and_or_b32 v154, v154, 15, v155
	s_mov_b64 s[14:15], -1
	v_ashrrev_i32_e32 v155, 31, v154
	s_cbranch_vccz .LBB0_1250
	v_lshlrev_b64 v[158:159], 12, v[154:155]
	s_mov_b32 s14, 0xfe000000
	v_lshl_add_u64 v[156:157], s[12:13], 0, v[158:159]
	s_mov_b32 s15, -1
	v_lshl_add_u64 v[156:157], v[156:157], 0, s[14:15]
	s_mov_b64 s[14:15], 0
